# row-sumsq words prefetched at tile header for GEMM1/3 + GEMM2/4 residual epilogue in register layout (no LDS staging, lane-pair exchange, all tile loads up front)
# baseline (speedup 1.0000x reference)
; #define LAS __attribute__((address_space(3)))
; __device__ __forceinline__ float bf_lo(unsigned w) { return __uint_as_float(w << 16); }
; __device__ __forceinline__ float bf_hi(unsigned w) { return __uint_as_float(w & 0xffff0000u); }
; __device__ __forceinline__ unsigned cvt_pk_bf16(float lo, float hi) { unsigned r; asm volatile("v_cvt_pk_bf16_f32 %0, %1, %2" : "=v"(r) : "v"(lo), "v"(hi)); return r; }
;     __device__ __forceinline__ void operator()(const f32x4 (&acc)[2][2][4][2], const Unit& u, int wr, int wc, int fr, int fq) const {
;         const int ln = fr + 16 * fq, rr = ln >> 3, cc = ln & 7; const int colw = u.pn * BM + 64 * wc;
;         LAS unsigned char* sl = stg + (wr * 4 + wc) * EPI_STG_SLICE;
; #pragma unroll
;         for (int ai = 0; ai < 2; ++ai) {
;             float qs[4];
; #pragma unroll
;             for (int mh = 0; mh < 2; ++mh) {
;             u32x4 bs[4][2];
; #pragma unroll
;             for (int m = 2 * mh; m < 2 * mh + 2; ++m) { const int rowb = u.pm * BM + ai * HALF + wr * 64 + m * 16;
; #pragma unroll
;                 for (int i = 0; i < 2; ++i) bs[m][i] = *(const u32x4*)(xb + (size_t)(rowb + rr + 8 * i) * DM + colw + cc * 8); }
; #pragma unroll
;             for (int m = 2 * mh; m < 2 * mh + 2; ++m) {
;                 const int rowb = u.pm * BM + ai * HALF + wr * 64 + m * 16; float q = 0.f;
; #pragma unroll
;                 for (int i = 0; i < 2; ++i) *(LAS u32x4*)(sl + (rr + 8 * i) * 144 + cc * 16) = bs[m][i];
; #pragma unroll
;                 for (int bj = 0; bj < 2; ++bj) {
;                     const u32x4 b4 = *(const LAS u32x4*)(sl + fr * 144 + bj * 64 + fq * 16);
;                     const f32x4 a0 = acc[ai][bj][m][0], a1 = acc[ai][bj][m][1];
;                     const float o0 = bf_lo(b4.x) + a0[0], o1 = bf_hi(b4.x) + a0[1], o2 = bf_lo(b4.y) + a0[2], o3 = bf_hi(b4.y) + a0[3];
;                     const float o4 = bf_lo(b4.z) + a1[0], o5 = bf_hi(b4.z) + a1[1], o6 = bf_lo(b4.w) + a1[2], o7 = bf_hi(b4.w) + a1[3];
;                     q += ((o0 * o0 + o1 * o1) + (o2 * o2 + o3 * o3)) + ((o4 * o4 + o5 * o5) + (o6 * o6 + o7 * o7));
;                     u32x4 w; w.x = cvt_pk_bf16(o0, o1); w.y = cvt_pk_bf16(o2, o3); w.z = cvt_pk_bf16(o4, o5); w.w = cvt_pk_bf16(o6, o7);
;                     *(LAS u32x4*)(sl + fr * 144 + bj * 64 + fq * 16) = w;
;                 }
.LBB0_429:
	s_lshl_b32 s2, s2, 8
	s_or_b32 s4, s2, s92
	s_lshl_b32 s2, s3, 8
	s_add_i32 s2, s2, s83
	s_lshl_b32 s7, s2, 11
	s_lshl_b32 s32, s4, 1
	s_add_u32 s7, s7, s32
	s_add_u32 s62, s44, s7
	s_addc_u32 s63, s45, 0
	v_and_b32_e32 v172, 15, v177
	v_bfe_u32 v173, v177, 4, 2
	v_lshlrev_b32_e32 v250, 11, v172
	v_lshl_add_u32 v250, v173, 4, v250
	v_and_b32_e32 v188, 1, v177
	v_and_b32_e32 v189, 14, v177
	v_cmp_eq_u32_e64 s[10:11], 0, v188
	v_lshlrev_b32_e32 v251, 11, v189
	v_lshl_add_u32 v251, v188, 6, v251
	v_lshl_add_u32 v251, v173, 4, v251
	v_add_u32_e32 v163, 0x800, v251
	s_mov_b32 s64, s62
	s_mov_b32 s65, s63
	global_load_dwordx4 v[206:209], v250, s[64:65]
	global_load_dwordx4 v[210:213], v250, s[64:65] offset:64
	s_add_u32 s64, s62, 0x8000
	s_addc_u32 s65, s63, 0
	global_load_dwordx4 v[214:217], v250, s[64:65]
	global_load_dwordx4 v[218:221], v250, s[64:65] offset:64
	s_add_u32 s64, s62, 0x10000
	s_addc_u32 s65, s63, 0
	global_load_dwordx4 v[222:225], v250, s[64:65]
	global_load_dwordx4 v[226:229], v250, s[64:65] offset:64
	s_add_u32 s64, s62, 0x18000
	s_addc_u32 s65, s63, 0
	global_load_dwordx4 v[230:233], v250, s[64:65]
	global_load_dwordx4 v[234:237], v250, s[64:65] offset:64
	s_add_u32 s64, s62, 0x40000
	s_addc_u32 s65, s63, 0
	global_load_dwordx4 v[238:241], v250, s[64:65]
	global_load_dwordx4 v[242:245], v250, s[64:65] offset:64
	s_add_u32 s64, s62, 0x48000
	s_addc_u32 s65, s63, 0
	global_load_dwordx4 v[246:249], v250, s[64:65]
	global_load_dwordx4 v[198:201], v250, s[64:65] offset:64
	s_add_u32 s64, s62, 0x50000
	s_addc_u32 s65, s63, 0
	global_load_dwordx4 v[202:205], v250, s[64:65]
	global_load_dwordx4 v[130:133], v250, s[64:65] offset:64
	s_add_u32 s64, s62, 0x58000
	s_addc_u32 s65, s63, 0
	global_load_dwordx4 v[134:137], v250, s[64:65]
	global_load_dwordx4 v[164:167], v250, s[64:65] offset:64
	s_waitcnt vmcnt(14)
	v_lshlrev_b32_e32 v172, 16, v206
	v_and_b32_e32 v173, 0xffff0000, v206
	v_add_f32_e32 v126, v126, v172
	v_add_f32_e32 v127, v127, v173
	v_lshlrev_b32_e32 v172, 16, v207
	v_and_b32_e32 v173, 0xffff0000, v207
	v_add_f32_e32 v128, v128, v172
	v_add_f32_e32 v129, v129, v173
	v_lshlrev_b32_e32 v172, 16, v208
	v_and_b32_e32 v173, 0xffff0000, v208
	v_add_f32_e32 v122, v122, v172
	v_add_f32_e32 v123, v123, v173
	v_lshlrev_b32_e32 v172, 16, v209
	v_and_b32_e32 v173, 0xffff0000, v209
	v_add_f32_e32 v124, v124, v172
	v_add_f32_e32 v125, v125, v173
	v_mul_f32_e32 v172, v127, v127
	v_mul_f32_e32 v173, v129, v129
	v_mul_f32_e32 v188, v123, v123
	v_mul_f32_e32 v189, v125, v125
	v_fmac_f32_e32 v172, v126, v126
	v_fmac_f32_e32 v173, v128, v128
	v_fmac_f32_e32 v188, v122, v122
	v_fmac_f32_e32 v189, v124, v124
	v_add_f32_e32 v172, v172, v173
	v_add_f32_e32 v188, v188, v189
	v_add_f32_e32 v172, v172, v188
	v_mov_b32_e32 v168, v172
	v_cvt_pk_bf16_f32 v126, v126, v127
	v_cvt_pk_bf16_f32 v127, v128, v129
	v_cvt_pk_bf16_f32 v128, v122, v123
	v_cvt_pk_bf16_f32 v129, v124, v125
	v_lshlrev_b32_e32 v172, 16, v210
	v_and_b32_e32 v173, 0xffff0000, v210
	v_add_f32_e32 v118, v118, v172
	v_add_f32_e32 v119, v119, v173
	v_lshlrev_b32_e32 v172, 16, v211
	v_and_b32_e32 v173, 0xffff0000, v211
	v_add_f32_e32 v120, v120, v172
	v_add_f32_e32 v121, v121, v173
	v_lshlrev_b32_e32 v172, 16, v212
	v_and_b32_e32 v173, 0xffff0000, v212
	v_add_f32_e32 v114, v114, v172
	v_add_f32_e32 v115, v115, v173
	v_lshlrev_b32_e32 v172, 16, v213
	v_and_b32_e32 v173, 0xffff0000, v213
	v_add_f32_e32 v116, v116, v172
	v_add_f32_e32 v117, v117, v173
	v_mul_f32_e32 v172, v119, v119
	v_mul_f32_e32 v173, v121, v121
	v_mul_f32_e32 v188, v115, v115
	v_mul_f32_e32 v189, v117, v117
	v_fmac_f32_e32 v172, v118, v118
	v_fmac_f32_e32 v173, v120, v120
	v_fmac_f32_e32 v188, v114, v114
	v_fmac_f32_e32 v189, v116, v116
	v_add_f32_e32 v172, v172, v173
	v_add_f32_e32 v188, v188, v189
	v_add_f32_e32 v172, v172, v188
	v_add_f32_e32 v168, v168, v172
	v_cvt_pk_bf16_f32 v118, v118, v119
	v_cvt_pk_bf16_f32 v119, v120, v121
	v_cvt_pk_bf16_f32 v120, v114, v115
	v_cvt_pk_bf16_f32 v121, v116, v117
	v_cndmask_b32_e64 v122, v126, v118, s[10:11]
	v_cndmask_b32_e64 v123, v127, v119, s[10:11]
	v_cndmask_b32_e64 v124, v128, v120, s[10:11]
	v_cndmask_b32_e64 v125, v129, v121, s[10:11]
	v_mov_b32_dpp v114, v122 quad_perm:[1,0,3,2] row_mask:0xf bank_mask:0xf
	v_mov_b32_dpp v115, v123 quad_perm:[1,0,3,2] row_mask:0xf bank_mask:0xf
	v_mov_b32_dpp v116, v124 quad_perm:[1,0,3,2] row_mask:0xf bank_mask:0xf
	v_mov_b32_dpp v117, v125 quad_perm:[1,0,3,2] row_mask:0xf bank_mask:0xf
	v_cndmask_b32_e64 v126, v114, v126, s[10:11]
	v_cndmask_b32_e64 v127, v115, v127, s[10:11]
	v_cndmask_b32_e64 v128, v116, v128, s[10:11]
	v_cndmask_b32_e64 v129, v117, v129, s[10:11]
	v_cndmask_b32_e64 v118, v118, v114, s[10:11]
	v_cndmask_b32_e64 v119, v119, v115, s[10:11]
	v_cndmask_b32_e64 v120, v120, v116, s[10:11]
	v_cndmask_b32_e64 v121, v121, v117, s[10:11]
	s_mov_b32 s64, s62
	s_mov_b32 s65, s63
	global_store_dwordx4 v251, v[126:129], s[64:65]
	global_store_dwordx4 v163, v[118:121], s[64:65]
	s_waitcnt vmcnt(14)
; #define LAS __attribute__((address_space(3)))
; __device__ __forceinline__ float bf_lo(unsigned w) { return __uint_as_float(w << 16); }
; __device__ __forceinline__ float bf_hi(unsigned w) { return __uint_as_float(w & 0xffff0000u); }
; __device__ __forceinline__ unsigned cvt_pk_bf16(float lo, float hi) { unsigned r; asm volatile("v_cvt_pk_bf16_f32 %0, %1, %2" : "=v"(r) : "v"(lo), "v"(hi)); return r; }
;     __device__ __forceinline__ void operator()(const f32x4 (&acc)[2][2][4][2], const Unit& u, int wr, int wc, int fr, int fq) const {
;     ...
;             for (int m = 2 * mh; m < 2 * mh + 2; ++m) { const int rowb = u.pm * BM + ai * HALF + wr * 64 + m * 16;
; #pragma unroll
;                 for (int i = 0; i < 2; ++i) bs[m][i] = *(const u32x4*)(xb + (size_t)(rowb + rr + 8 * i) * DM + colw + cc * 8); }
; #pragma unroll
;             for (int m = 2 * mh; m < 2 * mh + 2; ++m) {
;                 const int rowb = u.pm * BM + ai * HALF + wr * 64 + m * 16; float q = 0.f;
; #pragma unroll
;                 for (int i = 0; i < 2; ++i) *(LAS u32x4*)(sl + (rr + 8 * i) * 144 + cc * 16) = bs[m][i];
; #pragma unroll
;                 for (int bj = 0; bj < 2; ++bj) {
;                     const u32x4 b4 = *(const LAS u32x4*)(sl + fr * 144 + bj * 64 + fq * 16);
;                     const f32x4 a0 = acc[ai][bj][m][0], a1 = acc[ai][bj][m][1];
;                     const float o0 = bf_lo(b4.x) + a0[0], o1 = bf_hi(b4.x) + a0[1], o2 = bf_lo(b4.y) + a0[2], o3 = bf_hi(b4.y) + a0[3];
;                     const float o4 = bf_lo(b4.z) + a1[0], o5 = bf_hi(b4.z) + a1[1], o6 = bf_lo(b4.w) + a1[2], o7 = bf_hi(b4.w) + a1[3];
;                     q += ((o0 * o0 + o1 * o1) + (o2 * o2 + o3 * o3)) + ((o4 * o4 + o5 * o5) + (o6 * o6 + o7 * o7));
;                     u32x4 w; w.x = cvt_pk_bf16(o0, o1); w.y = cvt_pk_bf16(o2, o3); w.z = cvt_pk_bf16(o4, o5); w.w = cvt_pk_bf16(o6, o7);
;                     *(LAS u32x4*)(sl + fr * 144 + bj * 64 + fq * 16) = w;
;                 }
	v_lshlrev_b32_e32 v172, 16, v214
	v_and_b32_e32 v173, 0xffff0000, v214
	v_add_f32_e32 v110, v110, v172
	v_add_f32_e32 v111, v111, v173
	v_lshlrev_b32_e32 v172, 16, v215
	v_and_b32_e32 v173, 0xffff0000, v215
	v_add_f32_e32 v112, v112, v172
	v_add_f32_e32 v113, v113, v173
	v_lshlrev_b32_e32 v172, 16, v216
	v_and_b32_e32 v173, 0xffff0000, v216
	v_add_f32_e32 v106, v106, v172
	v_add_f32_e32 v107, v107, v173
	v_lshlrev_b32_e32 v172, 16, v217
	v_and_b32_e32 v173, 0xffff0000, v217
	v_add_f32_e32 v108, v108, v172
	v_add_f32_e32 v109, v109, v173
	v_mul_f32_e32 v172, v111, v111
	v_mul_f32_e32 v173, v113, v113
	v_mul_f32_e32 v188, v107, v107
	v_mul_f32_e32 v189, v109, v109
	v_fmac_f32_e32 v172, v110, v110
	v_fmac_f32_e32 v173, v112, v112
	v_fmac_f32_e32 v188, v106, v106
	v_fmac_f32_e32 v189, v108, v108
	v_add_f32_e32 v172, v172, v173
	v_add_f32_e32 v188, v188, v189
	v_add_f32_e32 v172, v172, v188
	v_mov_b32_e32 v169, v172
	v_cvt_pk_bf16_f32 v110, v110, v111
	v_cvt_pk_bf16_f32 v111, v112, v113
	v_cvt_pk_bf16_f32 v112, v106, v107
	v_cvt_pk_bf16_f32 v113, v108, v109
	v_lshlrev_b32_e32 v172, 16, v218
	v_and_b32_e32 v173, 0xffff0000, v218
	v_add_f32_e32 v102, v102, v172
	v_add_f32_e32 v103, v103, v173
	v_lshlrev_b32_e32 v172, 16, v219
	v_and_b32_e32 v173, 0xffff0000, v219
	v_add_f32_e32 v104, v104, v172
	v_add_f32_e32 v105, v105, v173
	v_lshlrev_b32_e32 v172, 16, v220
	v_and_b32_e32 v173, 0xffff0000, v220
	v_add_f32_e32 v98, v98, v172
	v_add_f32_e32 v99, v99, v173
	v_lshlrev_b32_e32 v172, 16, v221
	v_and_b32_e32 v173, 0xffff0000, v221
	v_add_f32_e32 v100, v100, v172
	v_add_f32_e32 v101, v101, v173
	v_mul_f32_e32 v172, v103, v103
	v_mul_f32_e32 v173, v105, v105
	v_mul_f32_e32 v188, v99, v99
	v_mul_f32_e32 v189, v101, v101
	v_fmac_f32_e32 v172, v102, v102
	v_fmac_f32_e32 v173, v104, v104
	v_fmac_f32_e32 v188, v98, v98
	v_fmac_f32_e32 v189, v100, v100
	v_add_f32_e32 v172, v172, v173
	v_add_f32_e32 v188, v188, v189
	v_add_f32_e32 v172, v172, v188
	v_add_f32_e32 v169, v169, v172
	v_cvt_pk_bf16_f32 v102, v102, v103
	v_cvt_pk_bf16_f32 v103, v104, v105
	v_cvt_pk_bf16_f32 v104, v98, v99
	v_cvt_pk_bf16_f32 v105, v100, v101
	v_cndmask_b32_e64 v106, v110, v102, s[10:11]
	v_cndmask_b32_e64 v107, v111, v103, s[10:11]
	v_cndmask_b32_e64 v108, v112, v104, s[10:11]
	v_cndmask_b32_e64 v109, v113, v105, s[10:11]
	v_mov_b32_dpp v98, v106 quad_perm:[1,0,3,2] row_mask:0xf bank_mask:0xf
	v_mov_b32_dpp v99, v107 quad_perm:[1,0,3,2] row_mask:0xf bank_mask:0xf
	v_mov_b32_dpp v100, v108 quad_perm:[1,0,3,2] row_mask:0xf bank_mask:0xf
	v_mov_b32_dpp v101, v109 quad_perm:[1,0,3,2] row_mask:0xf bank_mask:0xf
	v_cndmask_b32_e64 v110, v98, v110, s[10:11]
	v_cndmask_b32_e64 v111, v99, v111, s[10:11]
	v_cndmask_b32_e64 v112, v100, v112, s[10:11]
	v_cndmask_b32_e64 v113, v101, v113, s[10:11]
	v_cndmask_b32_e64 v102, v102, v98, s[10:11]
	v_cndmask_b32_e64 v103, v103, v99, s[10:11]
	v_cndmask_b32_e64 v104, v104, v100, s[10:11]
	v_cndmask_b32_e64 v105, v105, v101, s[10:11]
	s_add_u32 s64, s62, 0x8000
	s_addc_u32 s65, s63, 0
	global_store_dwordx4 v251, v[110:113], s[64:65]
	global_store_dwordx4 v163, v[102:105], s[64:65]
	s_waitcnt vmcnt(14)
	v_lshlrev_b32_e32 v172, 16, v222
	v_and_b32_e32 v173, 0xffff0000, v222
	v_add_f32_e32 v94, v94, v172
	v_add_f32_e32 v95, v95, v173
	v_lshlrev_b32_e32 v172, 16, v223
	v_and_b32_e32 v173, 0xffff0000, v223
	v_add_f32_e32 v96, v96, v172
	v_add_f32_e32 v97, v97, v173
	v_lshlrev_b32_e32 v172, 16, v224
	v_and_b32_e32 v173, 0xffff0000, v224
	v_add_f32_e32 v90, v90, v172
	v_add_f32_e32 v91, v91, v173
	v_lshlrev_b32_e32 v172, 16, v225
	v_and_b32_e32 v173, 0xffff0000, v225
	v_add_f32_e32 v92, v92, v172
	v_add_f32_e32 v93, v93, v173
	v_mul_f32_e32 v172, v95, v95
	v_mul_f32_e32 v173, v97, v97
	v_mul_f32_e32 v188, v91, v91
	v_mul_f32_e32 v189, v93, v93
	v_fmac_f32_e32 v172, v94, v94
	v_fmac_f32_e32 v173, v96, v96
	v_fmac_f32_e32 v188, v90, v90
	v_fmac_f32_e32 v189, v92, v92
	v_add_f32_e32 v172, v172, v173
	v_add_f32_e32 v188, v188, v189
	v_add_f32_e32 v172, v172, v188
	v_mov_b32_e32 v170, v172
	v_cvt_pk_bf16_f32 v94, v94, v95
	v_cvt_pk_bf16_f32 v95, v96, v97
	v_cvt_pk_bf16_f32 v96, v90, v91
	v_cvt_pk_bf16_f32 v97, v92, v93
	v_lshlrev_b32_e32 v172, 16, v226
	v_and_b32_e32 v173, 0xffff0000, v226
	v_add_f32_e32 v86, v86, v172
	v_add_f32_e32 v87, v87, v173
	v_lshlrev_b32_e32 v172, 16, v227
	v_and_b32_e32 v173, 0xffff0000, v227
	v_add_f32_e32 v88, v88, v172
	v_add_f32_e32 v89, v89, v173
	v_lshlrev_b32_e32 v172, 16, v228
	v_and_b32_e32 v173, 0xffff0000, v228
	v_add_f32_e32 v82, v82, v172
	v_add_f32_e32 v83, v83, v173
	v_lshlrev_b32_e32 v172, 16, v229
	v_and_b32_e32 v173, 0xffff0000, v229
	v_add_f32_e32 v84, v84, v172
	v_add_f32_e32 v85, v85, v173
	v_mul_f32_e32 v172, v87, v87
	v_mul_f32_e32 v173, v89, v89
	v_mul_f32_e32 v188, v83, v83
	v_mul_f32_e32 v189, v85, v85
	v_fmac_f32_e32 v172, v86, v86
	v_fmac_f32_e32 v173, v88, v88
	v_fmac_f32_e32 v188, v82, v82
	v_fmac_f32_e32 v189, v84, v84
	v_add_f32_e32 v172, v172, v173
	v_add_f32_e32 v188, v188, v189
	v_add_f32_e32 v172, v172, v188
	v_add_f32_e32 v170, v170, v172
	v_cvt_pk_bf16_f32 v86, v86, v87
	v_cvt_pk_bf16_f32 v87, v88, v89
	v_cvt_pk_bf16_f32 v88, v82, v83
	v_cvt_pk_bf16_f32 v89, v84, v85
	v_cndmask_b32_e64 v90, v94, v86, s[10:11]
	v_cndmask_b32_e64 v91, v95, v87, s[10:11]
	v_cndmask_b32_e64 v92, v96, v88, s[10:11]
	v_cndmask_b32_e64 v93, v97, v89, s[10:11]
	v_mov_b32_dpp v82, v90 quad_perm:[1,0,3,2] row_mask:0xf bank_mask:0xf
	v_mov_b32_dpp v83, v91 quad_perm:[1,0,3,2] row_mask:0xf bank_mask:0xf
	v_mov_b32_dpp v84, v92 quad_perm:[1,0,3,2] row_mask:0xf bank_mask:0xf
	v_mov_b32_dpp v85, v93 quad_perm:[1,0,3,2] row_mask:0xf bank_mask:0xf
	v_cndmask_b32_e64 v94, v82, v94, s[10:11]
	v_cndmask_b32_e64 v95, v83, v95, s[10:11]
	v_cndmask_b32_e64 v96, v84, v96, s[10:11]
	v_cndmask_b32_e64 v97, v85, v97, s[10:11]
	v_cndmask_b32_e64 v86, v86, v82, s[10:11]
	v_cndmask_b32_e64 v87, v87, v83, s[10:11]
	v_cndmask_b32_e64 v88, v88, v84, s[10:11]
	v_cndmask_b32_e64 v89, v89, v85, s[10:11]
	s_add_u32 s64, s62, 0x10000
	s_addc_u32 s65, s63, 0
	global_store_dwordx4 v251, v[94:97], s[64:65]
	global_store_dwordx4 v163, v[86:89], s[64:65]
	s_waitcnt vmcnt(14)
; #define LAS __attribute__((address_space(3)))
; __device__ __forceinline__ float bf_lo(unsigned w) { return __uint_as_float(w << 16); }
;     __device__ __forceinline__ void operator()(const f32x4 (&acc)[2][2][4][2], const Unit& u, int wr, int wc, int fr, int fq) const {
;     ...
;             for (int m = 2 * mh; m < 2 * mh + 2; ++m) { const int rowb = u.pm * BM + ai * HALF + wr * 64 + m * 16;
; #pragma unroll
;                 for (int i = 0; i < 2; ++i) bs[m][i] = *(const u32x4*)(xb + (size_t)(rowb + rr + 8 * i) * DM + colw + cc * 8); }
; #pragma unroll
;             for (int m = 2 * mh; m < 2 * mh + 2; ++m) {
;                 const int rowb = u.pm * BM + ai * HALF + wr * 64 + m * 16; float q = 0.f;
; #pragma unroll
;                 for (int i = 0; i < 2; ++i) *(LAS u32x4*)(sl + (rr + 8 * i) * 144 + cc * 16) = bs[m][i];
; #pragma unroll
;                 for (int bj = 0; bj < 2; ++bj) {
;                     const u32x4 b4 = *(const LAS u32x4*)(sl + fr * 144 + bj * 64 + fq * 16);
;                     const f32x4 a0 = acc[ai][bj][m][0], a1 = acc[ai][bj][m][1];
;                     const float o0 = bf_lo(b4.x) + a0[0], o1 = bf_hi(b4.x) + a0[1], o2 = bf_lo(b4.y) + a0[2], o3 = bf_hi(b4.y) + a0[3];
;                     const float o4 = bf_lo(b4.z) + a1[0], o5 = bf_hi(b4.z) + a1[1], o6 = bf_lo(b4.w) + a1[2], o7 = bf_hi(b4.w) + a1[3];
;                     q += ((o0 * o0 + o1 * o1) + (o2 * o2 + o3 * o3)) + ((o4 * o4 + o5 * o5) + (o6 * o6 + o7 * o7));
;                     u32x4 w; w.x = cvt_pk_bf16(o0, o1); w.y = cvt_pk_bf16(o2, o3); w.z = cvt_pk_bf16(o4, o5); w.w = cvt_pk_bf16(o6, o7);
;                     *(LAS u32x4*)(sl + fr * 144 + bj * 64 + fq * 16) = w;
;                 }
; #pragma unroll
;                 for (int i = 0; i < 2; ++i) { const u32x4 qv = *(const LAS u32x4*)(sl + (rr + 8 * i) * 144 + cc * 16);
;                     *(u32x4*)(xb + (size_t)(rowb + rr + 8 * i) * DM + colw + cc * 8) = qv; }
;                 q += __shfl_xor(q, 16); q += __shfl_xor(q, 32); qs[m] = q;
;             }
;             asm volatile("" ::: "memory");
;             }
;             { const float mine = fq == 0 ? qs[0] : (fq == 1 ? qs[1] : (fq == 2 ? qs[2] : qs[3]));
;               __hip_atomic_fetch_add(ssq + (u.pm * BM + ai * HALF + wr * 64 + 16 * fq + fr), (u64)(mine * 16777216.0f), __ATOMIC_RELAXED, __HIP_MEMORY_SCOPE_AGENT); }
	v_lshlrev_b32_e32 v172, 16, v230
	v_and_b32_e32 v173, 0xffff0000, v230
	v_add_f32_e32 v78, v78, v172
	v_add_f32_e32 v79, v79, v173
	v_lshlrev_b32_e32 v172, 16, v231
	v_and_b32_e32 v173, 0xffff0000, v231
	v_add_f32_e32 v80, v80, v172
	v_add_f32_e32 v81, v81, v173
	v_lshlrev_b32_e32 v172, 16, v232
	v_and_b32_e32 v173, 0xffff0000, v232
	v_add_f32_e32 v74, v74, v172
	v_add_f32_e32 v75, v75, v173
	v_lshlrev_b32_e32 v172, 16, v233
	v_and_b32_e32 v173, 0xffff0000, v233
	v_add_f32_e32 v76, v76, v172
	v_add_f32_e32 v77, v77, v173
	v_mul_f32_e32 v172, v79, v79
	v_mul_f32_e32 v173, v81, v81
	v_mul_f32_e32 v188, v75, v75
	v_mul_f32_e32 v189, v77, v77
	v_fmac_f32_e32 v172, v78, v78
	v_fmac_f32_e32 v173, v80, v80
	v_fmac_f32_e32 v188, v74, v74
	v_fmac_f32_e32 v189, v76, v76
	v_add_f32_e32 v172, v172, v173
	v_add_f32_e32 v188, v188, v189
	v_add_f32_e32 v172, v172, v188
	v_mov_b32_e32 v171, v172
	v_cvt_pk_bf16_f32 v78, v78, v79
	v_cvt_pk_bf16_f32 v79, v80, v81
	v_cvt_pk_bf16_f32 v80, v74, v75
	v_cvt_pk_bf16_f32 v81, v76, v77
	v_lshlrev_b32_e32 v172, 16, v234
	v_and_b32_e32 v173, 0xffff0000, v234
	v_add_f32_e32 v70, v70, v172
	v_add_f32_e32 v71, v71, v173
	v_lshlrev_b32_e32 v172, 16, v235
	v_and_b32_e32 v173, 0xffff0000, v235
	v_add_f32_e32 v72, v72, v172
	v_add_f32_e32 v73, v73, v173
	v_lshlrev_b32_e32 v172, 16, v236
	v_and_b32_e32 v173, 0xffff0000, v236
	v_add_f32_e32 v66, v66, v172
	v_add_f32_e32 v67, v67, v173
	v_lshlrev_b32_e32 v172, 16, v237
	v_and_b32_e32 v173, 0xffff0000, v237
	v_add_f32_e32 v68, v68, v172
	v_add_f32_e32 v69, v69, v173
	v_mul_f32_e32 v172, v71, v71
	v_mul_f32_e32 v173, v73, v73
	v_mul_f32_e32 v188, v67, v67
	v_mul_f32_e32 v189, v69, v69
	v_fmac_f32_e32 v172, v70, v70
	v_fmac_f32_e32 v173, v72, v72
	v_fmac_f32_e32 v188, v66, v66
	v_fmac_f32_e32 v189, v68, v68
	v_add_f32_e32 v172, v172, v173
	v_add_f32_e32 v188, v188, v189
	v_add_f32_e32 v172, v172, v188
	v_add_f32_e32 v171, v171, v172
	v_cvt_pk_bf16_f32 v70, v70, v71
	v_cvt_pk_bf16_f32 v71, v72, v73
	v_cvt_pk_bf16_f32 v72, v66, v67
	v_cvt_pk_bf16_f32 v73, v68, v69
	v_cndmask_b32_e64 v74, v78, v70, s[10:11]
	v_cndmask_b32_e64 v75, v79, v71, s[10:11]
	v_cndmask_b32_e64 v76, v80, v72, s[10:11]
	v_cndmask_b32_e64 v77, v81, v73, s[10:11]
	v_mov_b32_dpp v66, v74 quad_perm:[1,0,3,2] row_mask:0xf bank_mask:0xf
	v_mov_b32_dpp v67, v75 quad_perm:[1,0,3,2] row_mask:0xf bank_mask:0xf
	v_mov_b32_dpp v68, v76 quad_perm:[1,0,3,2] row_mask:0xf bank_mask:0xf
	v_mov_b32_dpp v69, v77 quad_perm:[1,0,3,2] row_mask:0xf bank_mask:0xf
	v_cndmask_b32_e64 v78, v66, v78, s[10:11]
	v_cndmask_b32_e64 v79, v67, v79, s[10:11]
	v_cndmask_b32_e64 v80, v68, v80, s[10:11]
	v_cndmask_b32_e64 v81, v69, v81, s[10:11]
	v_cndmask_b32_e64 v70, v70, v66, s[10:11]
	v_cndmask_b32_e64 v71, v71, v67, s[10:11]
	v_cndmask_b32_e64 v72, v72, v68, s[10:11]
	v_cndmask_b32_e64 v73, v73, v69, s[10:11]
	s_add_u32 s64, s62, 0x18000
	s_addc_u32 s65, s63, 0
	global_store_dwordx4 v251, v[78:81], s[64:65]
	global_store_dwordx4 v163, v[70:73], s[64:65]
	v_xor_b32_e32 v172, 16, v177
	v_lshlrev_b32_e32 v172, 2, v172
	v_xor_b32_e32 v173, 32, v177
	v_lshlrev_b32_e32 v173, 2, v173
	ds_bpermute_b32 v74, v172, v168
	ds_bpermute_b32 v75, v172, v169
	ds_bpermute_b32 v76, v172, v170
	ds_bpermute_b32 v77, v172, v171
	s_waitcnt lgkmcnt(3)
	v_add_f32_e32 v168, v168, v74
	s_waitcnt lgkmcnt(2)
	v_add_f32_e32 v169, v169, v75
	s_waitcnt lgkmcnt(1)
	v_add_f32_e32 v170, v170, v76
	s_waitcnt lgkmcnt(0)
	v_add_f32_e32 v171, v171, v77
	ds_bpermute_b32 v74, v173, v168
	ds_bpermute_b32 v75, v173, v169
	ds_bpermute_b32 v76, v173, v170
	ds_bpermute_b32 v77, v173, v171
	s_waitcnt lgkmcnt(3)
	v_add_f32_e32 v168, v168, v74
	s_waitcnt lgkmcnt(2)
	v_add_f32_e32 v169, v169, v75
	s_waitcnt lgkmcnt(1)
	v_add_f32_e32 v170, v170, v76
	s_waitcnt lgkmcnt(0)
	v_add_f32_e32 v171, v171, v77
	v_bfe_u32 v188, v177, 4, 2
	v_cmp_eq_u32_e64 s[64:65], 1, v188
	v_cmp_eq_u32_e64 s[98:99], 2, v188
	v_cmp_eq_u32_e32 vcc, 3, v188
	s_nop 1
	v_cndmask_b32_e64 v189, v168, v169, s[64:65]
	v_cndmask_b32_e64 v189, v189, v170, s[98:99]
	v_cndmask_b32_e32 v189, v189, v171, vcc
	v_mul_f32_e32 v189, 0x4b800000, v189
	v_trunc_f32_e32 v189, v189
	v_mul_f32_e32 v188, 0x2f800000, v189
	v_floor_f32_e32 v188, v188
	v_fmac_f32_e32 v189, 0xcf800000, v188
	v_cvt_u32_f32_e32 v172, v189
	v_cvt_u32_f32_e32 v173, v188
	s_lshl_b32 s7, s2, 3
	s_add_u32 s100, s46, s7
	s_addc_u32 s101, s47, 0
	v_lshlrev_b32_e32 v250, 3, v177
	global_atomic_add_x2 v250, v[172:173], s[100:101]
	s_waitcnt vmcnt(15)
; #define LAS __attribute__((address_space(3)))
; __device__ __forceinline__ float bf_lo(unsigned w) { return __uint_as_float(w << 16); }
; __device__ __forceinline__ float bf_hi(unsigned w) { return __uint_as_float(w & 0xffff0000u); }
; __device__ __forceinline__ unsigned cvt_pk_bf16(float lo, float hi) { unsigned r; asm volatile("v_cvt_pk_bf16_f32 %0, %1, %2" : "=v"(r) : "v"(lo), "v"(hi)); return r; }
;     __device__ __forceinline__ void operator()(const f32x4 (&acc)[2][2][4][2], const Unit& u, int wr, int wc, int fr, int fq) const {
;     ...
;             for (int m = 2 * mh; m < 2 * mh + 2; ++m) { const int rowb = u.pm * BM + ai * HALF + wr * 64 + m * 16;
; #pragma unroll
;                 for (int i = 0; i < 2; ++i) bs[m][i] = *(const u32x4*)(xb + (size_t)(rowb + rr + 8 * i) * DM + colw + cc * 8); }
; #pragma unroll
;             for (int m = 2 * mh; m < 2 * mh + 2; ++m) {
;                 const int rowb = u.pm * BM + ai * HALF + wr * 64 + m * 16; float q = 0.f;
; #pragma unroll
;                 for (int i = 0; i < 2; ++i) *(LAS u32x4*)(sl + (rr + 8 * i) * 144 + cc * 16) = bs[m][i];
; #pragma unroll
;                 for (int bj = 0; bj < 2; ++bj) {
;                     const u32x4 b4 = *(const LAS u32x4*)(sl + fr * 144 + bj * 64 + fq * 16);
;                     const f32x4 a0 = acc[ai][bj][m][0], a1 = acc[ai][bj][m][1];
;                     const float o0 = bf_lo(b4.x) + a0[0], o1 = bf_hi(b4.x) + a0[1], o2 = bf_lo(b4.y) + a0[2], o3 = bf_hi(b4.y) + a0[3];
;                     const float o4 = bf_lo(b4.z) + a1[0], o5 = bf_hi(b4.z) + a1[1], o6 = bf_lo(b4.w) + a1[2], o7 = bf_hi(b4.w) + a1[3];
;                     q += ((o0 * o0 + o1 * o1) + (o2 * o2 + o3 * o3)) + ((o4 * o4 + o5 * o5) + (o6 * o6 + o7 * o7));
;                     u32x4 w; w.x = cvt_pk_bf16(o0, o1); w.y = cvt_pk_bf16(o2, o3); w.z = cvt_pk_bf16(o4, o5); w.w = cvt_pk_bf16(o6, o7);
;                     *(LAS u32x4*)(sl + fr * 144 + bj * 64 + fq * 16) = w;
;                 }
	v_lshlrev_b32_e32 v172, 16, v238
	v_and_b32_e32 v173, 0xffff0000, v238
	v_add_f32_e32 v62, v62, v172
	v_add_f32_e32 v63, v63, v173
	v_lshlrev_b32_e32 v172, 16, v239
	v_and_b32_e32 v173, 0xffff0000, v239
	v_add_f32_e32 v64, v64, v172
	v_add_f32_e32 v65, v65, v173
	v_lshlrev_b32_e32 v172, 16, v240
	v_and_b32_e32 v173, 0xffff0000, v240
	v_add_f32_e32 v58, v58, v172
	v_add_f32_e32 v59, v59, v173
	v_lshlrev_b32_e32 v172, 16, v241
	v_and_b32_e32 v173, 0xffff0000, v241
	v_add_f32_e32 v60, v60, v172
	v_add_f32_e32 v61, v61, v173
	v_mul_f32_e32 v172, v63, v63
	v_mul_f32_e32 v173, v65, v65
	v_mul_f32_e32 v188, v59, v59
	v_mul_f32_e32 v189, v61, v61
	v_fmac_f32_e32 v172, v62, v62
	v_fmac_f32_e32 v173, v64, v64
	v_fmac_f32_e32 v188, v58, v58
	v_fmac_f32_e32 v189, v60, v60
	v_add_f32_e32 v172, v172, v173
	v_add_f32_e32 v188, v188, v189
	v_add_f32_e32 v172, v172, v188
	v_mov_b32_e32 v168, v172
	v_cvt_pk_bf16_f32 v62, v62, v63
	v_cvt_pk_bf16_f32 v63, v64, v65
	v_cvt_pk_bf16_f32 v64, v58, v59
	v_cvt_pk_bf16_f32 v65, v60, v61
	v_lshlrev_b32_e32 v172, 16, v242
	v_and_b32_e32 v173, 0xffff0000, v242
	v_add_f32_e32 v54, v54, v172
	v_add_f32_e32 v55, v55, v173
	v_lshlrev_b32_e32 v172, 16, v243
	v_and_b32_e32 v173, 0xffff0000, v243
	v_add_f32_e32 v56, v56, v172
	v_add_f32_e32 v57, v57, v173
	v_lshlrev_b32_e32 v172, 16, v244
	v_and_b32_e32 v173, 0xffff0000, v244
	v_add_f32_e32 v50, v50, v172
	v_add_f32_e32 v51, v51, v173
	v_lshlrev_b32_e32 v172, 16, v245
	v_and_b32_e32 v173, 0xffff0000, v245
	v_add_f32_e32 v52, v52, v172
	v_add_f32_e32 v53, v53, v173
	v_mul_f32_e32 v172, v55, v55
	v_mul_f32_e32 v173, v57, v57
	v_mul_f32_e32 v188, v51, v51
	v_mul_f32_e32 v189, v53, v53
	v_fmac_f32_e32 v172, v54, v54
	v_fmac_f32_e32 v173, v56, v56
	v_fmac_f32_e32 v188, v50, v50
	v_fmac_f32_e32 v189, v52, v52
	v_add_f32_e32 v172, v172, v173
	v_add_f32_e32 v188, v188, v189
	v_add_f32_e32 v172, v172, v188
	v_add_f32_e32 v168, v168, v172
	v_cvt_pk_bf16_f32 v54, v54, v55
	v_cvt_pk_bf16_f32 v55, v56, v57
	v_cvt_pk_bf16_f32 v56, v50, v51
	v_cvt_pk_bf16_f32 v57, v52, v53
	v_cndmask_b32_e64 v58, v62, v54, s[10:11]
	v_cndmask_b32_e64 v59, v63, v55, s[10:11]
	v_cndmask_b32_e64 v60, v64, v56, s[10:11]
	v_cndmask_b32_e64 v61, v65, v57, s[10:11]
	v_mov_b32_dpp v50, v58 quad_perm:[1,0,3,2] row_mask:0xf bank_mask:0xf
	v_mov_b32_dpp v51, v59 quad_perm:[1,0,3,2] row_mask:0xf bank_mask:0xf
	v_mov_b32_dpp v52, v60 quad_perm:[1,0,3,2] row_mask:0xf bank_mask:0xf
	v_mov_b32_dpp v53, v61 quad_perm:[1,0,3,2] row_mask:0xf bank_mask:0xf
	v_cndmask_b32_e64 v62, v50, v62, s[10:11]
	v_cndmask_b32_e64 v63, v51, v63, s[10:11]
	v_cndmask_b32_e64 v64, v52, v64, s[10:11]
	v_cndmask_b32_e64 v65, v53, v65, s[10:11]
	v_cndmask_b32_e64 v54, v54, v50, s[10:11]
	v_cndmask_b32_e64 v55, v55, v51, s[10:11]
	v_cndmask_b32_e64 v56, v56, v52, s[10:11]
	v_cndmask_b32_e64 v57, v57, v53, s[10:11]
	s_add_u32 s64, s62, 0x40000
	s_addc_u32 s65, s63, 0
	global_store_dwordx4 v251, v[62:65], s[64:65]
	global_store_dwordx4 v163, v[54:57], s[64:65]
	s_waitcnt vmcnt(15)
	v_lshlrev_b32_e32 v172, 16, v246
	v_and_b32_e32 v173, 0xffff0000, v246
	v_add_f32_e32 v46, v46, v172
	v_add_f32_e32 v47, v47, v173
	v_lshlrev_b32_e32 v172, 16, v247
	v_and_b32_e32 v173, 0xffff0000, v247
	v_add_f32_e32 v48, v48, v172
	v_add_f32_e32 v49, v49, v173
	v_lshlrev_b32_e32 v172, 16, v248
	v_and_b32_e32 v173, 0xffff0000, v248
	v_add_f32_e32 v42, v42, v172
	v_add_f32_e32 v43, v43, v173
	v_lshlrev_b32_e32 v172, 16, v249
	v_and_b32_e32 v173, 0xffff0000, v249
	v_add_f32_e32 v44, v44, v172
	v_add_f32_e32 v45, v45, v173
	v_mul_f32_e32 v172, v47, v47
	v_mul_f32_e32 v173, v49, v49
	v_mul_f32_e32 v188, v43, v43
	v_mul_f32_e32 v189, v45, v45
	v_fmac_f32_e32 v172, v46, v46
	v_fmac_f32_e32 v173, v48, v48
	v_fmac_f32_e32 v188, v42, v42
	v_fmac_f32_e32 v189, v44, v44
	v_add_f32_e32 v172, v172, v173
	v_add_f32_e32 v188, v188, v189
	v_add_f32_e32 v172, v172, v188
	v_mov_b32_e32 v169, v172
	v_cvt_pk_bf16_f32 v46, v46, v47
	v_cvt_pk_bf16_f32 v47, v48, v49
	v_cvt_pk_bf16_f32 v48, v42, v43
	v_cvt_pk_bf16_f32 v49, v44, v45
	v_lshlrev_b32_e32 v172, 16, v198
	v_and_b32_e32 v173, 0xffff0000, v198
	v_add_f32_e32 v38, v38, v172
	v_add_f32_e32 v39, v39, v173
	v_lshlrev_b32_e32 v172, 16, v199
	v_and_b32_e32 v173, 0xffff0000, v199
	v_add_f32_e32 v40, v40, v172
	v_add_f32_e32 v41, v41, v173
	v_lshlrev_b32_e32 v172, 16, v200
	v_and_b32_e32 v173, 0xffff0000, v200
	v_add_f32_e32 v34, v34, v172
	v_add_f32_e32 v35, v35, v173
	v_lshlrev_b32_e32 v172, 16, v201
	v_and_b32_e32 v173, 0xffff0000, v201
	v_add_f32_e32 v36, v36, v172
	v_add_f32_e32 v37, v37, v173
	v_mul_f32_e32 v172, v39, v39
	v_mul_f32_e32 v173, v41, v41
	v_mul_f32_e32 v188, v35, v35
	v_mul_f32_e32 v189, v37, v37
	v_fmac_f32_e32 v172, v38, v38
	v_fmac_f32_e32 v173, v40, v40
	v_fmac_f32_e32 v188, v34, v34
	v_fmac_f32_e32 v189, v36, v36
	v_add_f32_e32 v172, v172, v173
	v_add_f32_e32 v188, v188, v189
	v_add_f32_e32 v172, v172, v188
	v_add_f32_e32 v169, v169, v172
	v_cvt_pk_bf16_f32 v38, v38, v39
	v_cvt_pk_bf16_f32 v39, v40, v41
	v_cvt_pk_bf16_f32 v40, v34, v35
	v_cvt_pk_bf16_f32 v41, v36, v37
	v_cndmask_b32_e64 v42, v46, v38, s[10:11]
	v_cndmask_b32_e64 v43, v47, v39, s[10:11]
	v_cndmask_b32_e64 v44, v48, v40, s[10:11]
	v_cndmask_b32_e64 v45, v49, v41, s[10:11]
	v_mov_b32_dpp v34, v42 quad_perm:[1,0,3,2] row_mask:0xf bank_mask:0xf
	v_mov_b32_dpp v35, v43 quad_perm:[1,0,3,2] row_mask:0xf bank_mask:0xf
	v_mov_b32_dpp v36, v44 quad_perm:[1,0,3,2] row_mask:0xf bank_mask:0xf
	v_mov_b32_dpp v37, v45 quad_perm:[1,0,3,2] row_mask:0xf bank_mask:0xf
	v_cndmask_b32_e64 v46, v34, v46, s[10:11]
	v_cndmask_b32_e64 v47, v35, v47, s[10:11]
	v_cndmask_b32_e64 v48, v36, v48, s[10:11]
	v_cndmask_b32_e64 v49, v37, v49, s[10:11]
	v_cndmask_b32_e64 v38, v38, v34, s[10:11]
	v_cndmask_b32_e64 v39, v39, v35, s[10:11]
	v_cndmask_b32_e64 v40, v40, v36, s[10:11]
	v_cndmask_b32_e64 v41, v41, v37, s[10:11]
	s_add_u32 s64, s62, 0x48000
	s_addc_u32 s65, s63, 0
	global_store_dwordx4 v251, v[46:49], s[64:65]
	global_store_dwordx4 v163, v[38:41], s[64:65]
	s_waitcnt vmcnt(15)
; #define LAS __attribute__((address_space(3)))
; __device__ __forceinline__ float bf_lo(unsigned w) { return __uint_as_float(w << 16); }
; __device__ __forceinline__ float bf_hi(unsigned w) { return __uint_as_float(w & 0xffff0000u); }
; __device__ __forceinline__ unsigned cvt_pk_bf16(float lo, float hi) { unsigned r; asm volatile("v_cvt_pk_bf16_f32 %0, %1, %2" : "=v"(r) : "v"(lo), "v"(hi)); return r; }
;     __device__ __forceinline__ void operator()(const f32x4 (&acc)[2][2][4][2], const Unit& u, int wr, int wc, int fr, int fq) const {
;     ...
;             for (int m = 2 * mh; m < 2 * mh + 2; ++m) { const int rowb = u.pm * BM + ai * HALF + wr * 64 + m * 16;
; #pragma unroll
;                 for (int i = 0; i < 2; ++i) bs[m][i] = *(const u32x4*)(xb + (size_t)(rowb + rr + 8 * i) * DM + colw + cc * 8); }
; #pragma unroll
;             for (int m = 2 * mh; m < 2 * mh + 2; ++m) {
;                 const int rowb = u.pm * BM + ai * HALF + wr * 64 + m * 16; float q = 0.f;
; #pragma unroll
;                 for (int i = 0; i < 2; ++i) *(LAS u32x4*)(sl + (rr + 8 * i) * 144 + cc * 16) = bs[m][i];
; #pragma unroll
;                 for (int bj = 0; bj < 2; ++bj) {
;                     const u32x4 b4 = *(const LAS u32x4*)(sl + fr * 144 + bj * 64 + fq * 16);
;                     const f32x4 a0 = acc[ai][bj][m][0], a1 = acc[ai][bj][m][1];
;                     const float o0 = bf_lo(b4.x) + a0[0], o1 = bf_hi(b4.x) + a0[1], o2 = bf_lo(b4.y) + a0[2], o3 = bf_hi(b4.y) + a0[3];
;                     const float o4 = bf_lo(b4.z) + a1[0], o5 = bf_hi(b4.z) + a1[1], o6 = bf_lo(b4.w) + a1[2], o7 = bf_hi(b4.w) + a1[3];
;                     q += ((o0 * o0 + o1 * o1) + (o2 * o2 + o3 * o3)) + ((o4 * o4 + o5 * o5) + (o6 * o6 + o7 * o7));
;                     u32x4 w; w.x = cvt_pk_bf16(o0, o1); w.y = cvt_pk_bf16(o2, o3); w.z = cvt_pk_bf16(o4, o5); w.w = cvt_pk_bf16(o6, o7);
;                     *(LAS u32x4*)(sl + fr * 144 + bj * 64 + fq * 16) = w;
;                 }
	v_lshlrev_b32_e32 v172, 16, v202
	v_and_b32_e32 v173, 0xffff0000, v202
	v_add_f32_e32 v30, v30, v172
	v_add_f32_e32 v31, v31, v173
	v_lshlrev_b32_e32 v172, 16, v203
	v_and_b32_e32 v173, 0xffff0000, v203
	v_add_f32_e32 v32, v32, v172
	v_add_f32_e32 v33, v33, v173
	v_lshlrev_b32_e32 v172, 16, v204
	v_and_b32_e32 v173, 0xffff0000, v204
	v_add_f32_e32 v26, v26, v172
	v_add_f32_e32 v27, v27, v173
	v_lshlrev_b32_e32 v172, 16, v205
	v_and_b32_e32 v173, 0xffff0000, v205
	v_add_f32_e32 v28, v28, v172
	v_add_f32_e32 v29, v29, v173
	v_mul_f32_e32 v172, v31, v31
	v_mul_f32_e32 v173, v33, v33
	v_mul_f32_e32 v188, v27, v27
	v_mul_f32_e32 v189, v29, v29
	v_fmac_f32_e32 v172, v30, v30
	v_fmac_f32_e32 v173, v32, v32
	v_fmac_f32_e32 v188, v26, v26
	v_fmac_f32_e32 v189, v28, v28
	v_add_f32_e32 v172, v172, v173
	v_add_f32_e32 v188, v188, v189
	v_add_f32_e32 v172, v172, v188
	v_mov_b32_e32 v170, v172
	v_cvt_pk_bf16_f32 v30, v30, v31
	v_cvt_pk_bf16_f32 v31, v32, v33
	v_cvt_pk_bf16_f32 v32, v26, v27
	v_cvt_pk_bf16_f32 v33, v28, v29
	v_lshlrev_b32_e32 v172, 16, v130
	v_and_b32_e32 v173, 0xffff0000, v130
	v_add_f32_e32 v22, v22, v172
	v_add_f32_e32 v23, v23, v173
	v_lshlrev_b32_e32 v172, 16, v131
	v_and_b32_e32 v173, 0xffff0000, v131
	v_add_f32_e32 v24, v24, v172
	v_add_f32_e32 v25, v25, v173
	v_lshlrev_b32_e32 v172, 16, v132
	v_and_b32_e32 v173, 0xffff0000, v132
	v_add_f32_e32 v18, v18, v172
	v_add_f32_e32 v19, v19, v173
	v_lshlrev_b32_e32 v172, 16, v133
	v_and_b32_e32 v173, 0xffff0000, v133
	v_add_f32_e32 v20, v20, v172
	v_add_f32_e32 v21, v21, v173
	v_mul_f32_e32 v172, v23, v23
	v_mul_f32_e32 v173, v25, v25
	v_mul_f32_e32 v188, v19, v19
	v_mul_f32_e32 v189, v21, v21
	v_fmac_f32_e32 v172, v22, v22
	v_fmac_f32_e32 v173, v24, v24
	v_fmac_f32_e32 v188, v18, v18
	v_fmac_f32_e32 v189, v20, v20
	v_add_f32_e32 v172, v172, v173
	v_add_f32_e32 v188, v188, v189
	v_add_f32_e32 v172, v172, v188
	v_add_f32_e32 v170, v170, v172
	v_cvt_pk_bf16_f32 v22, v22, v23
	v_cvt_pk_bf16_f32 v23, v24, v25
	v_cvt_pk_bf16_f32 v24, v18, v19
	v_cvt_pk_bf16_f32 v25, v20, v21
	v_cndmask_b32_e64 v26, v30, v22, s[10:11]
	v_cndmask_b32_e64 v27, v31, v23, s[10:11]
	v_cndmask_b32_e64 v28, v32, v24, s[10:11]
	v_cndmask_b32_e64 v29, v33, v25, s[10:11]
	v_mov_b32_dpp v18, v26 quad_perm:[1,0,3,2] row_mask:0xf bank_mask:0xf
	v_mov_b32_dpp v19, v27 quad_perm:[1,0,3,2] row_mask:0xf bank_mask:0xf
	v_mov_b32_dpp v20, v28 quad_perm:[1,0,3,2] row_mask:0xf bank_mask:0xf
	v_mov_b32_dpp v21, v29 quad_perm:[1,0,3,2] row_mask:0xf bank_mask:0xf
	v_cndmask_b32_e64 v30, v18, v30, s[10:11]
	v_cndmask_b32_e64 v31, v19, v31, s[10:11]
	v_cndmask_b32_e64 v32, v20, v32, s[10:11]
	v_cndmask_b32_e64 v33, v21, v33, s[10:11]
	v_cndmask_b32_e64 v22, v22, v18, s[10:11]
	v_cndmask_b32_e64 v23, v23, v19, s[10:11]
	v_cndmask_b32_e64 v24, v24, v20, s[10:11]
	v_cndmask_b32_e64 v25, v25, v21, s[10:11]
	s_add_u32 s64, s62, 0x50000
	s_addc_u32 s65, s63, 0
	global_store_dwordx4 v251, v[30:33], s[64:65]
	global_store_dwordx4 v163, v[22:25], s[64:65]
	s_waitcnt vmcnt(15)
; #define LAS __attribute__((address_space(3)))
;     __device__ __forceinline__ void operator()(const f32x4 (&acc)[2][2][4][2], const Unit& u, int wr, int wc, int fr, int fq) const {
;     ...
;             for (int m = 2 * mh; m < 2 * mh + 2; ++m) { const int rowb = u.pm * BM + ai * HALF + wr * 64 + m * 16;
; #pragma unroll
;                 for (int i = 0; i < 2; ++i) bs[m][i] = *(const u32x4*)(xb + (size_t)(rowb + rr + 8 * i) * DM + colw + cc * 8); }
; #pragma unroll
;             for (int m = 2 * mh; m < 2 * mh + 2; ++m) {
;                 const int rowb = u.pm * BM + ai * HALF + wr * 64 + m * 16; float q = 0.f;
; #pragma unroll
;                 for (int i = 0; i < 2; ++i) *(LAS u32x4*)(sl + (rr + 8 * i) * 144 + cc * 16) = bs[m][i];
; #pragma unroll
;                 for (int bj = 0; bj < 2; ++bj) {
;                     const u32x4 b4 = *(const LAS u32x4*)(sl + fr * 144 + bj * 64 + fq * 16);
;                     const f32x4 a0 = acc[ai][bj][m][0], a1 = acc[ai][bj][m][1];
;                     const float o0 = bf_lo(b4.x) + a0[0], o1 = bf_hi(b4.x) + a0[1], o2 = bf_lo(b4.y) + a0[2], o3 = bf_hi(b4.y) + a0[3];
;                     const float o4 = bf_lo(b4.z) + a1[0], o5 = bf_hi(b4.z) + a1[1], o6 = bf_lo(b4.w) + a1[2], o7 = bf_hi(b4.w) + a1[3];
;                     q += ((o0 * o0 + o1 * o1) + (o2 * o2 + o3 * o3)) + ((o4 * o4 + o5 * o5) + (o6 * o6 + o7 * o7));
;                     u32x4 w; w.x = cvt_pk_bf16(o0, o1); w.y = cvt_pk_bf16(o2, o3); w.z = cvt_pk_bf16(o4, o5); w.w = cvt_pk_bf16(o6, o7);
;                     *(LAS u32x4*)(sl + fr * 144 + bj * 64 + fq * 16) = w;
;                 }
; #pragma unroll
;                 for (int i = 0; i < 2; ++i) { const u32x4 qv = *(const LAS u32x4*)(sl + (rr + 8 * i) * 144 + cc * 16);
;                     *(u32x4*)(xb + (size_t)(rowb + rr + 8 * i) * DM + colw + cc * 8) = qv; }
;                 q += __shfl_xor(q, 16); q += __shfl_xor(q, 32); qs[m] = q;
;             }
;             asm volatile("" ::: "memory");
;             }
;             { const float mine = fq == 0 ? qs[0] : (fq == 1 ? qs[1] : (fq == 2 ? qs[2] : qs[3]));
;               __hip_atomic_fetch_add(ssq + (u.pm * BM + ai * HALF + wr * 64 + 16 * fq + fr), (u64)(mine * 16777216.0f), __ATOMIC_RELAXED, __HIP_MEMORY_SCOPE_AGENT); }
;             asm volatile("" ::: "memory");
;         }
	v_lshlrev_b32_e32 v172, 16, v134
	v_and_b32_e32 v173, 0xffff0000, v134
	v_add_f32_e32 v14, v14, v172
	v_add_f32_e32 v15, v15, v173
	v_lshlrev_b32_e32 v172, 16, v135
	v_and_b32_e32 v173, 0xffff0000, v135
	v_add_f32_e32 v16, v16, v172
	v_add_f32_e32 v17, v17, v173
	v_lshlrev_b32_e32 v172, 16, v136
	v_and_b32_e32 v173, 0xffff0000, v136
	v_add_f32_e32 v10, v10, v172
	v_add_f32_e32 v11, v11, v173
	v_lshlrev_b32_e32 v172, 16, v137
	v_and_b32_e32 v173, 0xffff0000, v137
	v_add_f32_e32 v12, v12, v172
	v_add_f32_e32 v13, v13, v173
	v_mul_f32_e32 v172, v15, v15
	v_mul_f32_e32 v173, v17, v17
	v_mul_f32_e32 v188, v11, v11
	v_mul_f32_e32 v189, v13, v13
	v_fmac_f32_e32 v172, v14, v14
	v_fmac_f32_e32 v173, v16, v16
	v_fmac_f32_e32 v188, v10, v10
	v_fmac_f32_e32 v189, v12, v12
	v_add_f32_e32 v172, v172, v173
	v_add_f32_e32 v188, v188, v189
	v_add_f32_e32 v172, v172, v188
	v_mov_b32_e32 v171, v172
	v_cvt_pk_bf16_f32 v14, v14, v15
	v_cvt_pk_bf16_f32 v15, v16, v17
	v_cvt_pk_bf16_f32 v16, v10, v11
	v_cvt_pk_bf16_f32 v17, v12, v13
	v_lshlrev_b32_e32 v172, 16, v164
	v_and_b32_e32 v173, 0xffff0000, v164
	v_add_f32_e32 v6, v6, v172
	v_add_f32_e32 v7, v7, v173
	v_lshlrev_b32_e32 v172, 16, v165
	v_and_b32_e32 v173, 0xffff0000, v165
	v_add_f32_e32 v8, v8, v172
	v_add_f32_e32 v9, v9, v173
	v_lshlrev_b32_e32 v172, 16, v166
	v_and_b32_e32 v173, 0xffff0000, v166
	v_add_f32_e32 v2, v2, v172
	v_add_f32_e32 v3, v3, v173
	v_lshlrev_b32_e32 v172, 16, v167
	v_and_b32_e32 v173, 0xffff0000, v167
	v_add_f32_e32 v4, v4, v172
	v_add_f32_e32 v5, v5, v173
	v_mul_f32_e32 v172, v7, v7
	v_mul_f32_e32 v173, v9, v9
	v_mul_f32_e32 v188, v3, v3
	v_mul_f32_e32 v189, v5, v5
	v_fmac_f32_e32 v172, v6, v6
	v_fmac_f32_e32 v173, v8, v8
	v_fmac_f32_e32 v188, v2, v2
	v_fmac_f32_e32 v189, v4, v4
	v_add_f32_e32 v172, v172, v173
	v_add_f32_e32 v188, v188, v189
	v_add_f32_e32 v172, v172, v188
	v_add_f32_e32 v171, v171, v172
	v_cvt_pk_bf16_f32 v6, v6, v7
	v_cvt_pk_bf16_f32 v7, v8, v9
	v_cvt_pk_bf16_f32 v8, v2, v3
	v_cvt_pk_bf16_f32 v9, v4, v5
	v_cndmask_b32_e64 v10, v14, v6, s[10:11]
	v_cndmask_b32_e64 v11, v15, v7, s[10:11]
	v_cndmask_b32_e64 v12, v16, v8, s[10:11]
	v_cndmask_b32_e64 v13, v17, v9, s[10:11]
	v_mov_b32_dpp v2, v10 quad_perm:[1,0,3,2] row_mask:0xf bank_mask:0xf
	v_mov_b32_dpp v3, v11 quad_perm:[1,0,3,2] row_mask:0xf bank_mask:0xf
	v_mov_b32_dpp v4, v12 quad_perm:[1,0,3,2] row_mask:0xf bank_mask:0xf
	v_mov_b32_dpp v5, v13 quad_perm:[1,0,3,2] row_mask:0xf bank_mask:0xf
	v_cndmask_b32_e64 v14, v2, v14, s[10:11]
	v_cndmask_b32_e64 v15, v3, v15, s[10:11]
	v_cndmask_b32_e64 v16, v4, v16, s[10:11]
	v_cndmask_b32_e64 v17, v5, v17, s[10:11]
	v_cndmask_b32_e64 v6, v6, v2, s[10:11]
	v_cndmask_b32_e64 v7, v7, v3, s[10:11]
	v_cndmask_b32_e64 v8, v8, v4, s[10:11]
	v_cndmask_b32_e64 v9, v9, v5, s[10:11]
	s_add_u32 s64, s62, 0x58000
	s_addc_u32 s65, s63, 0
	global_store_dwordx4 v251, v[14:17], s[64:65]
	global_store_dwordx4 v163, v[6:9], s[64:65]
	v_xor_b32_e32 v172, 16, v177
	v_lshlrev_b32_e32 v172, 2, v172
	v_xor_b32_e32 v173, 32, v177
	v_lshlrev_b32_e32 v173, 2, v173
	ds_bpermute_b32 v10, v172, v168
	ds_bpermute_b32 v11, v172, v169
	ds_bpermute_b32 v12, v172, v170
	ds_bpermute_b32 v13, v172, v171
	s_waitcnt lgkmcnt(3)
	v_add_f32_e32 v168, v168, v10
	s_waitcnt lgkmcnt(2)
	v_add_f32_e32 v169, v169, v11
	s_waitcnt lgkmcnt(1)
	v_add_f32_e32 v170, v170, v12
	s_waitcnt lgkmcnt(0)
	v_add_f32_e32 v171, v171, v13
	ds_bpermute_b32 v10, v173, v168
	ds_bpermute_b32 v11, v173, v169
	ds_bpermute_b32 v12, v173, v170
	ds_bpermute_b32 v13, v173, v171
	s_waitcnt lgkmcnt(3)
	v_add_f32_e32 v168, v168, v10
	s_waitcnt lgkmcnt(2)
	v_add_f32_e32 v169, v169, v11
	s_waitcnt lgkmcnt(1)
	v_add_f32_e32 v170, v170, v12
	s_waitcnt lgkmcnt(0)
	v_add_f32_e32 v171, v171, v13
	v_bfe_u32 v188, v177, 4, 2
	v_cmp_eq_u32_e64 s[64:65], 1, v188
	v_cmp_eq_u32_e64 s[98:99], 2, v188
	v_cmp_eq_u32_e32 vcc, 3, v188
	s_nop 1
	v_cndmask_b32_e64 v189, v168, v169, s[64:65]
	v_cndmask_b32_e64 v189, v189, v170, s[98:99]
	v_cndmask_b32_e32 v189, v189, v171, vcc
	v_mul_f32_e32 v189, 0x4b800000, v189
	v_trunc_f32_e32 v189, v189
	v_mul_f32_e32 v188, 0x2f800000, v189
	v_floor_f32_e32 v188, v188
	v_fmac_f32_e32 v189, 0xcf800000, v188
	v_cvt_u32_f32_e32 v172, v189
	v_cvt_u32_f32_e32 v173, v188
	s_andn2_b64 vcc, exec, s[40:41]
	s_mov_b64 s[26:27], -1
	global_atomic_add_x2 v250, v[172:173], s[100:101] offset:1024
	s_cbranch_vccnz .LBB0_418
	s_andn2_b64 vcc, exec, s[42:43]
	s_cbranch_vccnz .LBB0_417
	s_barrier
	s_branch .LBB0_417

; #define LAS __attribute__((address_space(3)))
; __device__ __forceinline__ float bf_lo(unsigned w) { return __uint_as_float(w << 16); }
; __device__ __forceinline__ float bf_hi(unsigned w) { return __uint_as_float(w & 0xffff0000u); }
; __device__ __forceinline__ unsigned cvt_pk_bf16(float lo, float hi) { unsigned r; asm volatile("v_cvt_pk_bf16_f32 %0, %1, %2" : "=v"(r) : "v"(lo), "v"(hi)); return r; }
;     __device__ __forceinline__ void operator()(const f32x4 (&acc)[2][2][4][2], const Unit& u, int wr, int wc, int fr, int fq) const {
;         const int ln = fr + 16 * fq, rr = ln >> 3, cc = ln & 7; const int colw = u.pn * BM + 64 * wc;
;         LAS unsigned char* sl = stg + (wr * 4 + wc) * EPI_STG_SLICE;
; #pragma unroll
;         for (int ai = 0; ai < 2; ++ai) {
;             float qs[4];
; #pragma unroll
;             for (int mh = 0; mh < 2; ++mh) {
;             u32x4 bs[4][2];
; #pragma unroll
;             for (int m = 2 * mh; m < 2 * mh + 2; ++m) { const int rowb = u.pm * BM + ai * HALF + wr * 64 + m * 16;
; #pragma unroll
;                 for (int i = 0; i < 2; ++i) bs[m][i] = *(const u32x4*)(xb + (size_t)(rowb + rr + 8 * i) * DM + colw + cc * 8); }
; #pragma unroll
;             for (int m = 2 * mh; m < 2 * mh + 2; ++m) {
;                 const int rowb = u.pm * BM + ai * HALF + wr * 64 + m * 16; float q = 0.f;
; #pragma unroll
;                 for (int i = 0; i < 2; ++i) *(LAS u32x4*)(sl + (rr + 8 * i) * 144 + cc * 16) = bs[m][i];
; #pragma unroll
;                 for (int bj = 0; bj < 2; ++bj) {
;                     const u32x4 b4 = *(const LAS u32x4*)(sl + fr * 144 + bj * 64 + fq * 16);
;                     const f32x4 a0 = acc[ai][bj][m][0], a1 = acc[ai][bj][m][1];
;                     const float o0 = bf_lo(b4.x) + a0[0], o1 = bf_hi(b4.x) + a0[1], o2 = bf_lo(b4.y) + a0[2], o3 = bf_hi(b4.y) + a0[3];
;                     const float o4 = bf_lo(b4.z) + a1[0], o5 = bf_hi(b4.z) + a1[1], o6 = bf_lo(b4.w) + a1[2], o7 = bf_hi(b4.w) + a1[3];
;                     q += ((o0 * o0 + o1 * o1) + (o2 * o2 + o3 * o3)) + ((o4 * o4 + o5 * o5) + (o6 * o6 + o7 * o7));
;                     u32x4 w; w.x = cvt_pk_bf16(o0, o1); w.y = cvt_pk_bf16(o2, o3); w.z = cvt_pk_bf16(o4, o5); w.w = cvt_pk_bf16(o6, o7);
;                     *(LAS u32x4*)(sl + fr * 144 + bj * 64 + fq * 16) = w;
;                 }
.LBB0_591:
	s_lshl_b32 s2, s2, 8
	s_or_b32 s4, s2, s82
	s_lshl_b32 s2, s3, 8
	s_add_i32 s2, s2, s79
	s_lshl_b32 s7, s2, 11
	s_lshl_b32 s32, s4, 1
	s_add_u32 s7, s7, s32
	s_add_u32 s62, s40, s7
	s_addc_u32 s63, s41, 0
	v_and_b32_e32 v172, 15, v177
	v_bfe_u32 v173, v177, 4, 2
	v_lshlrev_b32_e32 v250, 11, v172
	v_lshl_add_u32 v250, v173, 4, v250
	v_and_b32_e32 v188, 1, v177
	v_and_b32_e32 v189, 14, v177
	v_cmp_eq_u32_e64 s[10:11], 0, v188
	v_lshlrev_b32_e32 v251, 11, v189
	v_lshl_add_u32 v251, v188, 6, v251
	v_lshl_add_u32 v251, v173, 4, v251
	v_add_u32_e32 v163, 0x800, v251
	s_mov_b32 s64, s62
	s_mov_b32 s65, s63
	global_load_dwordx4 v[206:209], v250, s[64:65]
	global_load_dwordx4 v[210:213], v250, s[64:65] offset:64
	s_add_u32 s64, s62, 0x8000
	s_addc_u32 s65, s63, 0
	global_load_dwordx4 v[214:217], v250, s[64:65]
	global_load_dwordx4 v[218:221], v250, s[64:65] offset:64
	s_add_u32 s64, s62, 0x10000
	s_addc_u32 s65, s63, 0
	global_load_dwordx4 v[222:225], v250, s[64:65]
	global_load_dwordx4 v[226:229], v250, s[64:65] offset:64
	s_add_u32 s64, s62, 0x18000
	s_addc_u32 s65, s63, 0
	global_load_dwordx4 v[230:233], v250, s[64:65]
	global_load_dwordx4 v[234:237], v250, s[64:65] offset:64
	s_add_u32 s64, s62, 0x40000
	s_addc_u32 s65, s63, 0
	global_load_dwordx4 v[238:241], v250, s[64:65]
	global_load_dwordx4 v[242:245], v250, s[64:65] offset:64
	s_add_u32 s64, s62, 0x48000
	s_addc_u32 s65, s63, 0
	global_load_dwordx4 v[246:249], v250, s[64:65]
	global_load_dwordx4 v[198:201], v250, s[64:65] offset:64
	s_add_u32 s64, s62, 0x50000
	s_addc_u32 s65, s63, 0
	global_load_dwordx4 v[202:205], v250, s[64:65]
	global_load_dwordx4 v[130:133], v250, s[64:65] offset:64
	s_add_u32 s64, s62, 0x58000
	s_addc_u32 s65, s63, 0
	global_load_dwordx4 v[134:137], v250, s[64:65]
	global_load_dwordx4 v[164:167], v250, s[64:65] offset:64
	s_waitcnt vmcnt(14)
	v_lshlrev_b32_e32 v172, 16, v206
	v_and_b32_e32 v173, 0xffff0000, v206
	v_add_f32_e32 v126, v126, v172
	v_add_f32_e32 v127, v127, v173
	v_lshlrev_b32_e32 v172, 16, v207
	v_and_b32_e32 v173, 0xffff0000, v207
	v_add_f32_e32 v128, v128, v172
	v_add_f32_e32 v129, v129, v173
	v_lshlrev_b32_e32 v172, 16, v208
	v_and_b32_e32 v173, 0xffff0000, v208
	v_add_f32_e32 v122, v122, v172
	v_add_f32_e32 v123, v123, v173
	v_lshlrev_b32_e32 v172, 16, v209
	v_and_b32_e32 v173, 0xffff0000, v209
	v_add_f32_e32 v124, v124, v172
	v_add_f32_e32 v125, v125, v173
	v_mul_f32_e32 v172, v127, v127
	v_mul_f32_e32 v173, v129, v129
	v_mul_f32_e32 v188, v123, v123
	v_mul_f32_e32 v189, v125, v125
	v_fmac_f32_e32 v172, v126, v126
	v_fmac_f32_e32 v173, v128, v128
	v_fmac_f32_e32 v188, v122, v122
	v_fmac_f32_e32 v189, v124, v124
	v_add_f32_e32 v172, v172, v173
	v_add_f32_e32 v188, v188, v189
	v_add_f32_e32 v172, v172, v188
	v_mov_b32_e32 v168, v172
	v_cvt_pk_bf16_f32 v126, v126, v127
	v_cvt_pk_bf16_f32 v127, v128, v129
	v_cvt_pk_bf16_f32 v128, v122, v123
	v_cvt_pk_bf16_f32 v129, v124, v125
	v_lshlrev_b32_e32 v172, 16, v210
	v_and_b32_e32 v173, 0xffff0000, v210
	v_add_f32_e32 v118, v118, v172
	v_add_f32_e32 v119, v119, v173
	v_lshlrev_b32_e32 v172, 16, v211
	v_and_b32_e32 v173, 0xffff0000, v211
	v_add_f32_e32 v120, v120, v172
	v_add_f32_e32 v121, v121, v173
	v_lshlrev_b32_e32 v172, 16, v212
	v_and_b32_e32 v173, 0xffff0000, v212
	v_add_f32_e32 v114, v114, v172
	v_add_f32_e32 v115, v115, v173
	v_lshlrev_b32_e32 v172, 16, v213
	v_and_b32_e32 v173, 0xffff0000, v213
	v_add_f32_e32 v116, v116, v172
	v_add_f32_e32 v117, v117, v173
	v_mul_f32_e32 v172, v119, v119
	v_mul_f32_e32 v173, v121, v121
	v_mul_f32_e32 v188, v115, v115
	v_mul_f32_e32 v189, v117, v117
	v_fmac_f32_e32 v172, v118, v118
	v_fmac_f32_e32 v173, v120, v120
	v_fmac_f32_e32 v188, v114, v114
	v_fmac_f32_e32 v189, v116, v116
	v_add_f32_e32 v172, v172, v173
	v_add_f32_e32 v188, v188, v189
	v_add_f32_e32 v172, v172, v188
	v_add_f32_e32 v168, v168, v172
	v_cvt_pk_bf16_f32 v118, v118, v119
	v_cvt_pk_bf16_f32 v119, v120, v121
	v_cvt_pk_bf16_f32 v120, v114, v115
	v_cvt_pk_bf16_f32 v121, v116, v117
	v_cndmask_b32_e64 v122, v126, v118, s[10:11]
	v_cndmask_b32_e64 v123, v127, v119, s[10:11]
	v_cndmask_b32_e64 v124, v128, v120, s[10:11]
	v_cndmask_b32_e64 v125, v129, v121, s[10:11]
	v_mov_b32_dpp v114, v122 quad_perm:[1,0,3,2] row_mask:0xf bank_mask:0xf
	v_mov_b32_dpp v115, v123 quad_perm:[1,0,3,2] row_mask:0xf bank_mask:0xf
	v_mov_b32_dpp v116, v124 quad_perm:[1,0,3,2] row_mask:0xf bank_mask:0xf
	v_mov_b32_dpp v117, v125 quad_perm:[1,0,3,2] row_mask:0xf bank_mask:0xf
	v_cndmask_b32_e64 v126, v114, v126, s[10:11]
	v_cndmask_b32_e64 v127, v115, v127, s[10:11]
	v_cndmask_b32_e64 v128, v116, v128, s[10:11]
	v_cndmask_b32_e64 v129, v117, v129, s[10:11]
	v_cndmask_b32_e64 v118, v118, v114, s[10:11]
	v_cndmask_b32_e64 v119, v119, v115, s[10:11]
	v_cndmask_b32_e64 v120, v120, v116, s[10:11]
	v_cndmask_b32_e64 v121, v121, v117, s[10:11]
	s_mov_b32 s64, s62
	s_mov_b32 s65, s63
	global_store_dwordx4 v251, v[126:129], s[64:65]
	global_store_dwordx4 v163, v[118:121], s[64:65]
	s_waitcnt vmcnt(14)
; #define LAS __attribute__((address_space(3)))
; __device__ __forceinline__ float bf_lo(unsigned w) { return __uint_as_float(w << 16); }
; __device__ __forceinline__ float bf_hi(unsigned w) { return __uint_as_float(w & 0xffff0000u); }
; __device__ __forceinline__ unsigned cvt_pk_bf16(float lo, float hi) { unsigned r; asm volatile("v_cvt_pk_bf16_f32 %0, %1, %2" : "=v"(r) : "v"(lo), "v"(hi)); return r; }
;     __device__ __forceinline__ void operator()(const f32x4 (&acc)[2][2][4][2], const Unit& u, int wr, int wc, int fr, int fq) const {
;     ...
;             for (int m = 2 * mh; m < 2 * mh + 2; ++m) { const int rowb = u.pm * BM + ai * HALF + wr * 64 + m * 16;
; #pragma unroll
;                 for (int i = 0; i < 2; ++i) bs[m][i] = *(const u32x4*)(xb + (size_t)(rowb + rr + 8 * i) * DM + colw + cc * 8); }
; #pragma unroll
;             for (int m = 2 * mh; m < 2 * mh + 2; ++m) {
;                 const int rowb = u.pm * BM + ai * HALF + wr * 64 + m * 16; float q = 0.f;
; #pragma unroll
;                 for (int i = 0; i < 2; ++i) *(LAS u32x4*)(sl + (rr + 8 * i) * 144 + cc * 16) = bs[m][i];
; #pragma unroll
;                 for (int bj = 0; bj < 2; ++bj) {
;                     const u32x4 b4 = *(const LAS u32x4*)(sl + fr * 144 + bj * 64 + fq * 16);
;                     const f32x4 a0 = acc[ai][bj][m][0], a1 = acc[ai][bj][m][1];
;                     const float o0 = bf_lo(b4.x) + a0[0], o1 = bf_hi(b4.x) + a0[1], o2 = bf_lo(b4.y) + a0[2], o3 = bf_hi(b4.y) + a0[3];
;                     const float o4 = bf_lo(b4.z) + a1[0], o5 = bf_hi(b4.z) + a1[1], o6 = bf_lo(b4.w) + a1[2], o7 = bf_hi(b4.w) + a1[3];
;                     q += ((o0 * o0 + o1 * o1) + (o2 * o2 + o3 * o3)) + ((o4 * o4 + o5 * o5) + (o6 * o6 + o7 * o7));
;                     u32x4 w; w.x = cvt_pk_bf16(o0, o1); w.y = cvt_pk_bf16(o2, o3); w.z = cvt_pk_bf16(o4, o5); w.w = cvt_pk_bf16(o6, o7);
;                     *(LAS u32x4*)(sl + fr * 144 + bj * 64 + fq * 16) = w;
;                 }
	v_lshlrev_b32_e32 v172, 16, v214
	v_and_b32_e32 v173, 0xffff0000, v214
	v_add_f32_e32 v110, v110, v172
	v_add_f32_e32 v111, v111, v173
	v_lshlrev_b32_e32 v172, 16, v215
	v_and_b32_e32 v173, 0xffff0000, v215
	v_add_f32_e32 v112, v112, v172
	v_add_f32_e32 v113, v113, v173
	v_lshlrev_b32_e32 v172, 16, v216
	v_and_b32_e32 v173, 0xffff0000, v216
	v_add_f32_e32 v106, v106, v172
	v_add_f32_e32 v107, v107, v173
	v_lshlrev_b32_e32 v172, 16, v217
	v_and_b32_e32 v173, 0xffff0000, v217
	v_add_f32_e32 v108, v108, v172
	v_add_f32_e32 v109, v109, v173
	v_mul_f32_e32 v172, v111, v111
	v_mul_f32_e32 v173, v113, v113
	v_mul_f32_e32 v188, v107, v107
	v_mul_f32_e32 v189, v109, v109
	v_fmac_f32_e32 v172, v110, v110
	v_fmac_f32_e32 v173, v112, v112
	v_fmac_f32_e32 v188, v106, v106
	v_fmac_f32_e32 v189, v108, v108
	v_add_f32_e32 v172, v172, v173
	v_add_f32_e32 v188, v188, v189
	v_add_f32_e32 v172, v172, v188
	v_mov_b32_e32 v169, v172
	v_cvt_pk_bf16_f32 v110, v110, v111
	v_cvt_pk_bf16_f32 v111, v112, v113
	v_cvt_pk_bf16_f32 v112, v106, v107
	v_cvt_pk_bf16_f32 v113, v108, v109
	v_lshlrev_b32_e32 v172, 16, v218
	v_and_b32_e32 v173, 0xffff0000, v218
	v_add_f32_e32 v102, v102, v172
	v_add_f32_e32 v103, v103, v173
	v_lshlrev_b32_e32 v172, 16, v219
	v_and_b32_e32 v173, 0xffff0000, v219
	v_add_f32_e32 v104, v104, v172
	v_add_f32_e32 v105, v105, v173
	v_lshlrev_b32_e32 v172, 16, v220
	v_and_b32_e32 v173, 0xffff0000, v220
	v_add_f32_e32 v98, v98, v172
	v_add_f32_e32 v99, v99, v173
	v_lshlrev_b32_e32 v172, 16, v221
	v_and_b32_e32 v173, 0xffff0000, v221
	v_add_f32_e32 v100, v100, v172
	v_add_f32_e32 v101, v101, v173
	v_mul_f32_e32 v172, v103, v103
	v_mul_f32_e32 v173, v105, v105
	v_mul_f32_e32 v188, v99, v99
	v_mul_f32_e32 v189, v101, v101
	v_fmac_f32_e32 v172, v102, v102
	v_fmac_f32_e32 v173, v104, v104
	v_fmac_f32_e32 v188, v98, v98
	v_fmac_f32_e32 v189, v100, v100
	v_add_f32_e32 v172, v172, v173
	v_add_f32_e32 v188, v188, v189
	v_add_f32_e32 v172, v172, v188
	v_add_f32_e32 v169, v169, v172
	v_cvt_pk_bf16_f32 v102, v102, v103
	v_cvt_pk_bf16_f32 v103, v104, v105
	v_cvt_pk_bf16_f32 v104, v98, v99
	v_cvt_pk_bf16_f32 v105, v100, v101
	v_cndmask_b32_e64 v106, v110, v102, s[10:11]
	v_cndmask_b32_e64 v107, v111, v103, s[10:11]
	v_cndmask_b32_e64 v108, v112, v104, s[10:11]
	v_cndmask_b32_e64 v109, v113, v105, s[10:11]
	v_mov_b32_dpp v98, v106 quad_perm:[1,0,3,2] row_mask:0xf bank_mask:0xf
	v_mov_b32_dpp v99, v107 quad_perm:[1,0,3,2] row_mask:0xf bank_mask:0xf
	v_mov_b32_dpp v100, v108 quad_perm:[1,0,3,2] row_mask:0xf bank_mask:0xf
	v_mov_b32_dpp v101, v109 quad_perm:[1,0,3,2] row_mask:0xf bank_mask:0xf
	v_cndmask_b32_e64 v110, v98, v110, s[10:11]
	v_cndmask_b32_e64 v111, v99, v111, s[10:11]
	v_cndmask_b32_e64 v112, v100, v112, s[10:11]
	v_cndmask_b32_e64 v113, v101, v113, s[10:11]
	v_cndmask_b32_e64 v102, v102, v98, s[10:11]
	v_cndmask_b32_e64 v103, v103, v99, s[10:11]
	v_cndmask_b32_e64 v104, v104, v100, s[10:11]
	v_cndmask_b32_e64 v105, v105, v101, s[10:11]
	s_add_u32 s64, s62, 0x8000
	s_addc_u32 s65, s63, 0
	global_store_dwordx4 v251, v[110:113], s[64:65]
	global_store_dwordx4 v163, v[102:105], s[64:65]
	s_waitcnt vmcnt(14)
	v_lshlrev_b32_e32 v172, 16, v222
	v_and_b32_e32 v173, 0xffff0000, v222
	v_add_f32_e32 v94, v94, v172
	v_add_f32_e32 v95, v95, v173
	v_lshlrev_b32_e32 v172, 16, v223
	v_and_b32_e32 v173, 0xffff0000, v223
	v_add_f32_e32 v96, v96, v172
	v_add_f32_e32 v97, v97, v173
	v_lshlrev_b32_e32 v172, 16, v224
	v_and_b32_e32 v173, 0xffff0000, v224
	v_add_f32_e32 v90, v90, v172
	v_add_f32_e32 v91, v91, v173
	v_lshlrev_b32_e32 v172, 16, v225
	v_and_b32_e32 v173, 0xffff0000, v225
	v_add_f32_e32 v92, v92, v172
	v_add_f32_e32 v93, v93, v173
	v_mul_f32_e32 v172, v95, v95
	v_mul_f32_e32 v173, v97, v97
	v_mul_f32_e32 v188, v91, v91
	v_mul_f32_e32 v189, v93, v93
	v_fmac_f32_e32 v172, v94, v94
	v_fmac_f32_e32 v173, v96, v96
	v_fmac_f32_e32 v188, v90, v90
	v_fmac_f32_e32 v189, v92, v92
	v_add_f32_e32 v172, v172, v173
	v_add_f32_e32 v188, v188, v189
	v_add_f32_e32 v172, v172, v188
	v_mov_b32_e32 v170, v172
	v_cvt_pk_bf16_f32 v94, v94, v95
	v_cvt_pk_bf16_f32 v95, v96, v97
	v_cvt_pk_bf16_f32 v96, v90, v91
	v_cvt_pk_bf16_f32 v97, v92, v93
	v_lshlrev_b32_e32 v172, 16, v226
	v_and_b32_e32 v173, 0xffff0000, v226
	v_add_f32_e32 v86, v86, v172
	v_add_f32_e32 v87, v87, v173
	v_lshlrev_b32_e32 v172, 16, v227
	v_and_b32_e32 v173, 0xffff0000, v227
	v_add_f32_e32 v88, v88, v172
	v_add_f32_e32 v89, v89, v173
	v_lshlrev_b32_e32 v172, 16, v228
	v_and_b32_e32 v173, 0xffff0000, v228
	v_add_f32_e32 v82, v82, v172
	v_add_f32_e32 v83, v83, v173
	v_lshlrev_b32_e32 v172, 16, v229
	v_and_b32_e32 v173, 0xffff0000, v229
	v_add_f32_e32 v84, v84, v172
	v_add_f32_e32 v85, v85, v173
	v_mul_f32_e32 v172, v87, v87
	v_mul_f32_e32 v173, v89, v89
	v_mul_f32_e32 v188, v83, v83
	v_mul_f32_e32 v189, v85, v85
	v_fmac_f32_e32 v172, v86, v86
	v_fmac_f32_e32 v173, v88, v88
	v_fmac_f32_e32 v188, v82, v82
	v_fmac_f32_e32 v189, v84, v84
	v_add_f32_e32 v172, v172, v173
	v_add_f32_e32 v188, v188, v189
	v_add_f32_e32 v172, v172, v188
	v_add_f32_e32 v170, v170, v172
	v_cvt_pk_bf16_f32 v86, v86, v87
	v_cvt_pk_bf16_f32 v87, v88, v89
	v_cvt_pk_bf16_f32 v88, v82, v83
	v_cvt_pk_bf16_f32 v89, v84, v85
	v_cndmask_b32_e64 v90, v94, v86, s[10:11]
	v_cndmask_b32_e64 v91, v95, v87, s[10:11]
	v_cndmask_b32_e64 v92, v96, v88, s[10:11]
	v_cndmask_b32_e64 v93, v97, v89, s[10:11]
	v_mov_b32_dpp v82, v90 quad_perm:[1,0,3,2] row_mask:0xf bank_mask:0xf
	v_mov_b32_dpp v83, v91 quad_perm:[1,0,3,2] row_mask:0xf bank_mask:0xf
	v_mov_b32_dpp v84, v92 quad_perm:[1,0,3,2] row_mask:0xf bank_mask:0xf
	v_mov_b32_dpp v85, v93 quad_perm:[1,0,3,2] row_mask:0xf bank_mask:0xf
	v_cndmask_b32_e64 v94, v82, v94, s[10:11]
	v_cndmask_b32_e64 v95, v83, v95, s[10:11]
	v_cndmask_b32_e64 v96, v84, v96, s[10:11]
	v_cndmask_b32_e64 v97, v85, v97, s[10:11]
	v_cndmask_b32_e64 v86, v86, v82, s[10:11]
	v_cndmask_b32_e64 v87, v87, v83, s[10:11]
	v_cndmask_b32_e64 v88, v88, v84, s[10:11]
	v_cndmask_b32_e64 v89, v89, v85, s[10:11]
	s_add_u32 s64, s62, 0x10000
	s_addc_u32 s65, s63, 0
	global_store_dwordx4 v251, v[94:97], s[64:65]
	global_store_dwordx4 v163, v[86:89], s[64:65]
	s_waitcnt vmcnt(14)
; #define LAS __attribute__((address_space(3)))
; __device__ __forceinline__ float bf_lo(unsigned w) { return __uint_as_float(w << 16); }
;     __device__ __forceinline__ void operator()(const f32x4 (&acc)[2][2][4][2], const Unit& u, int wr, int wc, int fr, int fq) const {
;     ...
;             for (int m = 2 * mh; m < 2 * mh + 2; ++m) { const int rowb = u.pm * BM + ai * HALF + wr * 64 + m * 16;
; #pragma unroll
;                 for (int i = 0; i < 2; ++i) bs[m][i] = *(const u32x4*)(xb + (size_t)(rowb + rr + 8 * i) * DM + colw + cc * 8); }
; #pragma unroll
;             for (int m = 2 * mh; m < 2 * mh + 2; ++m) {
;                 const int rowb = u.pm * BM + ai * HALF + wr * 64 + m * 16; float q = 0.f;
; #pragma unroll
;                 for (int i = 0; i < 2; ++i) *(LAS u32x4*)(sl + (rr + 8 * i) * 144 + cc * 16) = bs[m][i];
; #pragma unroll
;                 for (int bj = 0; bj < 2; ++bj) {
;                     const u32x4 b4 = *(const LAS u32x4*)(sl + fr * 144 + bj * 64 + fq * 16);
;                     const f32x4 a0 = acc[ai][bj][m][0], a1 = acc[ai][bj][m][1];
;                     const float o0 = bf_lo(b4.x) + a0[0], o1 = bf_hi(b4.x) + a0[1], o2 = bf_lo(b4.y) + a0[2], o3 = bf_hi(b4.y) + a0[3];
;                     const float o4 = bf_lo(b4.z) + a1[0], o5 = bf_hi(b4.z) + a1[1], o6 = bf_lo(b4.w) + a1[2], o7 = bf_hi(b4.w) + a1[3];
;                     q += ((o0 * o0 + o1 * o1) + (o2 * o2 + o3 * o3)) + ((o4 * o4 + o5 * o5) + (o6 * o6 + o7 * o7));
;                     u32x4 w; w.x = cvt_pk_bf16(o0, o1); w.y = cvt_pk_bf16(o2, o3); w.z = cvt_pk_bf16(o4, o5); w.w = cvt_pk_bf16(o6, o7);
;                     *(LAS u32x4*)(sl + fr * 144 + bj * 64 + fq * 16) = w;
;                 }
; #pragma unroll
;                 for (int i = 0; i < 2; ++i) { const u32x4 qv = *(const LAS u32x4*)(sl + (rr + 8 * i) * 144 + cc * 16);
;                     *(u32x4*)(xb + (size_t)(rowb + rr + 8 * i) * DM + colw + cc * 8) = qv; }
;                 q += __shfl_xor(q, 16); q += __shfl_xor(q, 32); qs[m] = q;
;             }
;             asm volatile("" ::: "memory");
;             }
;             { const float mine = fq == 0 ? qs[0] : (fq == 1 ? qs[1] : (fq == 2 ? qs[2] : qs[3]));
;               __hip_atomic_fetch_add(ssq + (u.pm * BM + ai * HALF + wr * 64 + 16 * fq + fr), (u64)(mine * 16777216.0f), __ATOMIC_RELAXED, __HIP_MEMORY_SCOPE_AGENT); }
	v_lshlrev_b32_e32 v172, 16, v230
	v_and_b32_e32 v173, 0xffff0000, v230
	v_add_f32_e32 v78, v78, v172
	v_add_f32_e32 v79, v79, v173
	v_lshlrev_b32_e32 v172, 16, v231
	v_and_b32_e32 v173, 0xffff0000, v231
	v_add_f32_e32 v80, v80, v172
	v_add_f32_e32 v81, v81, v173
	v_lshlrev_b32_e32 v172, 16, v232
	v_and_b32_e32 v173, 0xffff0000, v232
	v_add_f32_e32 v74, v74, v172
	v_add_f32_e32 v75, v75, v173
	v_lshlrev_b32_e32 v172, 16, v233
	v_and_b32_e32 v173, 0xffff0000, v233
	v_add_f32_e32 v76, v76, v172
	v_add_f32_e32 v77, v77, v173
	v_mul_f32_e32 v172, v79, v79
	v_mul_f32_e32 v173, v81, v81
	v_mul_f32_e32 v188, v75, v75
	v_mul_f32_e32 v189, v77, v77
	v_fmac_f32_e32 v172, v78, v78
	v_fmac_f32_e32 v173, v80, v80
	v_fmac_f32_e32 v188, v74, v74
	v_fmac_f32_e32 v189, v76, v76
	v_add_f32_e32 v172, v172, v173
	v_add_f32_e32 v188, v188, v189
	v_add_f32_e32 v172, v172, v188
	v_mov_b32_e32 v171, v172
	v_cvt_pk_bf16_f32 v78, v78, v79
	v_cvt_pk_bf16_f32 v79, v80, v81
	v_cvt_pk_bf16_f32 v80, v74, v75
	v_cvt_pk_bf16_f32 v81, v76, v77
	v_lshlrev_b32_e32 v172, 16, v234
	v_and_b32_e32 v173, 0xffff0000, v234
	v_add_f32_e32 v70, v70, v172
	v_add_f32_e32 v71, v71, v173
	v_lshlrev_b32_e32 v172, 16, v235
	v_and_b32_e32 v173, 0xffff0000, v235
	v_add_f32_e32 v72, v72, v172
	v_add_f32_e32 v73, v73, v173
	v_lshlrev_b32_e32 v172, 16, v236
	v_and_b32_e32 v173, 0xffff0000, v236
	v_add_f32_e32 v66, v66, v172
	v_add_f32_e32 v67, v67, v173
	v_lshlrev_b32_e32 v172, 16, v237
	v_and_b32_e32 v173, 0xffff0000, v237
	v_add_f32_e32 v68, v68, v172
	v_add_f32_e32 v69, v69, v173
	v_mul_f32_e32 v172, v71, v71
	v_mul_f32_e32 v173, v73, v73
	v_mul_f32_e32 v188, v67, v67
	v_mul_f32_e32 v189, v69, v69
	v_fmac_f32_e32 v172, v70, v70
	v_fmac_f32_e32 v173, v72, v72
	v_fmac_f32_e32 v188, v66, v66
	v_fmac_f32_e32 v189, v68, v68
	v_add_f32_e32 v172, v172, v173
	v_add_f32_e32 v188, v188, v189
	v_add_f32_e32 v172, v172, v188
	v_add_f32_e32 v171, v171, v172
	v_cvt_pk_bf16_f32 v70, v70, v71
	v_cvt_pk_bf16_f32 v71, v72, v73
	v_cvt_pk_bf16_f32 v72, v66, v67
	v_cvt_pk_bf16_f32 v73, v68, v69
	v_cndmask_b32_e64 v74, v78, v70, s[10:11]
	v_cndmask_b32_e64 v75, v79, v71, s[10:11]
	v_cndmask_b32_e64 v76, v80, v72, s[10:11]
	v_cndmask_b32_e64 v77, v81, v73, s[10:11]
	v_mov_b32_dpp v66, v74 quad_perm:[1,0,3,2] row_mask:0xf bank_mask:0xf
	v_mov_b32_dpp v67, v75 quad_perm:[1,0,3,2] row_mask:0xf bank_mask:0xf
	v_mov_b32_dpp v68, v76 quad_perm:[1,0,3,2] row_mask:0xf bank_mask:0xf
	v_mov_b32_dpp v69, v77 quad_perm:[1,0,3,2] row_mask:0xf bank_mask:0xf
	v_cndmask_b32_e64 v78, v66, v78, s[10:11]
	v_cndmask_b32_e64 v79, v67, v79, s[10:11]
	v_cndmask_b32_e64 v80, v68, v80, s[10:11]
	v_cndmask_b32_e64 v81, v69, v81, s[10:11]
	v_cndmask_b32_e64 v70, v70, v66, s[10:11]
	v_cndmask_b32_e64 v71, v71, v67, s[10:11]
	v_cndmask_b32_e64 v72, v72, v68, s[10:11]
	v_cndmask_b32_e64 v73, v73, v69, s[10:11]
	s_add_u32 s64, s62, 0x18000
	s_addc_u32 s65, s63, 0
	global_store_dwordx4 v251, v[78:81], s[64:65]
	global_store_dwordx4 v163, v[70:73], s[64:65]
	v_xor_b32_e32 v172, 16, v177
	v_lshlrev_b32_e32 v172, 2, v172
	v_xor_b32_e32 v173, 32, v177
	v_lshlrev_b32_e32 v173, 2, v173
	ds_bpermute_b32 v74, v172, v168
	ds_bpermute_b32 v75, v172, v169
	ds_bpermute_b32 v76, v172, v170
	ds_bpermute_b32 v77, v172, v171
	s_waitcnt lgkmcnt(3)
	v_add_f32_e32 v168, v168, v74
	s_waitcnt lgkmcnt(2)
	v_add_f32_e32 v169, v169, v75
	s_waitcnt lgkmcnt(1)
	v_add_f32_e32 v170, v170, v76
	s_waitcnt lgkmcnt(0)
	v_add_f32_e32 v171, v171, v77
	ds_bpermute_b32 v74, v173, v168
	ds_bpermute_b32 v75, v173, v169
	ds_bpermute_b32 v76, v173, v170
	ds_bpermute_b32 v77, v173, v171
	s_waitcnt lgkmcnt(3)
	v_add_f32_e32 v168, v168, v74
	s_waitcnt lgkmcnt(2)
	v_add_f32_e32 v169, v169, v75
	s_waitcnt lgkmcnt(1)
	v_add_f32_e32 v170, v170, v76
	s_waitcnt lgkmcnt(0)
	v_add_f32_e32 v171, v171, v77
	v_bfe_u32 v188, v177, 4, 2
	v_cmp_eq_u32_e64 s[64:65], 1, v188
	v_cmp_eq_u32_e64 s[98:99], 2, v188
	v_cmp_eq_u32_e32 vcc, 3, v188
	s_nop 1
	v_cndmask_b32_e64 v189, v168, v169, s[64:65]
	v_cndmask_b32_e64 v189, v189, v170, s[98:99]
	v_cndmask_b32_e32 v189, v189, v171, vcc
	v_mul_f32_e32 v189, 0x4b800000, v189
	v_trunc_f32_e32 v189, v189
	v_mul_f32_e32 v188, 0x2f800000, v189
	v_floor_f32_e32 v188, v188
	v_fmac_f32_e32 v189, 0xcf800000, v188
	v_cvt_u32_f32_e32 v172, v189
	v_cvt_u32_f32_e32 v173, v188
	s_lshl_b32 s7, s2, 3
	s_add_u32 s100, s42, s7
	s_addc_u32 s101, s43, 0
	v_lshlrev_b32_e32 v250, 3, v177
	global_atomic_add_x2 v250, v[172:173], s[100:101]
	s_waitcnt vmcnt(15)
; #define LAS __attribute__((address_space(3)))
; __device__ __forceinline__ float bf_lo(unsigned w) { return __uint_as_float(w << 16); }
; __device__ __forceinline__ float bf_hi(unsigned w) { return __uint_as_float(w & 0xffff0000u); }
; __device__ __forceinline__ unsigned cvt_pk_bf16(float lo, float hi) { unsigned r; asm volatile("v_cvt_pk_bf16_f32 %0, %1, %2" : "=v"(r) : "v"(lo), "v"(hi)); return r; }
;     __device__ __forceinline__ void operator()(const f32x4 (&acc)[2][2][4][2], const Unit& u, int wr, int wc, int fr, int fq) const {
;     ...
;             for (int m = 2 * mh; m < 2 * mh + 2; ++m) { const int rowb = u.pm * BM + ai * HALF + wr * 64 + m * 16;
; #pragma unroll
;                 for (int i = 0; i < 2; ++i) bs[m][i] = *(const u32x4*)(xb + (size_t)(rowb + rr + 8 * i) * DM + colw + cc * 8); }
; #pragma unroll
;             for (int m = 2 * mh; m < 2 * mh + 2; ++m) {
;                 const int rowb = u.pm * BM + ai * HALF + wr * 64 + m * 16; float q = 0.f;
; #pragma unroll
;                 for (int i = 0; i < 2; ++i) *(LAS u32x4*)(sl + (rr + 8 * i) * 144 + cc * 16) = bs[m][i];
; #pragma unroll
;                 for (int bj = 0; bj < 2; ++bj) {
;                     const u32x4 b4 = *(const LAS u32x4*)(sl + fr * 144 + bj * 64 + fq * 16);
;                     const f32x4 a0 = acc[ai][bj][m][0], a1 = acc[ai][bj][m][1];
;                     const float o0 = bf_lo(b4.x) + a0[0], o1 = bf_hi(b4.x) + a0[1], o2 = bf_lo(b4.y) + a0[2], o3 = bf_hi(b4.y) + a0[3];
;                     const float o4 = bf_lo(b4.z) + a1[0], o5 = bf_hi(b4.z) + a1[1], o6 = bf_lo(b4.w) + a1[2], o7 = bf_hi(b4.w) + a1[3];
;                     q += ((o0 * o0 + o1 * o1) + (o2 * o2 + o3 * o3)) + ((o4 * o4 + o5 * o5) + (o6 * o6 + o7 * o7));
;                     u32x4 w; w.x = cvt_pk_bf16(o0, o1); w.y = cvt_pk_bf16(o2, o3); w.z = cvt_pk_bf16(o4, o5); w.w = cvt_pk_bf16(o6, o7);
;                     *(LAS u32x4*)(sl + fr * 144 + bj * 64 + fq * 16) = w;
;                 }
	v_lshlrev_b32_e32 v172, 16, v238
	v_and_b32_e32 v173, 0xffff0000, v238
	v_add_f32_e32 v62, v62, v172
	v_add_f32_e32 v63, v63, v173
	v_lshlrev_b32_e32 v172, 16, v239
	v_and_b32_e32 v173, 0xffff0000, v239
	v_add_f32_e32 v64, v64, v172
	v_add_f32_e32 v65, v65, v173
	v_lshlrev_b32_e32 v172, 16, v240
	v_and_b32_e32 v173, 0xffff0000, v240
	v_add_f32_e32 v58, v58, v172
	v_add_f32_e32 v59, v59, v173
	v_lshlrev_b32_e32 v172, 16, v241
	v_and_b32_e32 v173, 0xffff0000, v241
	v_add_f32_e32 v60, v60, v172
	v_add_f32_e32 v61, v61, v173
	v_mul_f32_e32 v172, v63, v63
	v_mul_f32_e32 v173, v65, v65
	v_mul_f32_e32 v188, v59, v59
	v_mul_f32_e32 v189, v61, v61
	v_fmac_f32_e32 v172, v62, v62
	v_fmac_f32_e32 v173, v64, v64
	v_fmac_f32_e32 v188, v58, v58
	v_fmac_f32_e32 v189, v60, v60
	v_add_f32_e32 v172, v172, v173
	v_add_f32_e32 v188, v188, v189
	v_add_f32_e32 v172, v172, v188
	v_mov_b32_e32 v168, v172
	v_cvt_pk_bf16_f32 v62, v62, v63
	v_cvt_pk_bf16_f32 v63, v64, v65
	v_cvt_pk_bf16_f32 v64, v58, v59
	v_cvt_pk_bf16_f32 v65, v60, v61
	v_lshlrev_b32_e32 v172, 16, v242
	v_and_b32_e32 v173, 0xffff0000, v242
	v_add_f32_e32 v54, v54, v172
	v_add_f32_e32 v55, v55, v173
	v_lshlrev_b32_e32 v172, 16, v243
	v_and_b32_e32 v173, 0xffff0000, v243
	v_add_f32_e32 v56, v56, v172
	v_add_f32_e32 v57, v57, v173
	v_lshlrev_b32_e32 v172, 16, v244
	v_and_b32_e32 v173, 0xffff0000, v244
	v_add_f32_e32 v50, v50, v172
	v_add_f32_e32 v51, v51, v173
	v_lshlrev_b32_e32 v172, 16, v245
	v_and_b32_e32 v173, 0xffff0000, v245
	v_add_f32_e32 v52, v52, v172
	v_add_f32_e32 v53, v53, v173
	v_mul_f32_e32 v172, v55, v55
	v_mul_f32_e32 v173, v57, v57
	v_mul_f32_e32 v188, v51, v51
	v_mul_f32_e32 v189, v53, v53
	v_fmac_f32_e32 v172, v54, v54
	v_fmac_f32_e32 v173, v56, v56
	v_fmac_f32_e32 v188, v50, v50
	v_fmac_f32_e32 v189, v52, v52
	v_add_f32_e32 v172, v172, v173
	v_add_f32_e32 v188, v188, v189
	v_add_f32_e32 v172, v172, v188
	v_add_f32_e32 v168, v168, v172
	v_cvt_pk_bf16_f32 v54, v54, v55
	v_cvt_pk_bf16_f32 v55, v56, v57
	v_cvt_pk_bf16_f32 v56, v50, v51
	v_cvt_pk_bf16_f32 v57, v52, v53
	v_cndmask_b32_e64 v58, v62, v54, s[10:11]
	v_cndmask_b32_e64 v59, v63, v55, s[10:11]
	v_cndmask_b32_e64 v60, v64, v56, s[10:11]
	v_cndmask_b32_e64 v61, v65, v57, s[10:11]
	v_mov_b32_dpp v50, v58 quad_perm:[1,0,3,2] row_mask:0xf bank_mask:0xf
	v_mov_b32_dpp v51, v59 quad_perm:[1,0,3,2] row_mask:0xf bank_mask:0xf
	v_mov_b32_dpp v52, v60 quad_perm:[1,0,3,2] row_mask:0xf bank_mask:0xf
	v_mov_b32_dpp v53, v61 quad_perm:[1,0,3,2] row_mask:0xf bank_mask:0xf
	v_cndmask_b32_e64 v62, v50, v62, s[10:11]
	v_cndmask_b32_e64 v63, v51, v63, s[10:11]
	v_cndmask_b32_e64 v64, v52, v64, s[10:11]
	v_cndmask_b32_e64 v65, v53, v65, s[10:11]
	v_cndmask_b32_e64 v54, v54, v50, s[10:11]
	v_cndmask_b32_e64 v55, v55, v51, s[10:11]
	v_cndmask_b32_e64 v56, v56, v52, s[10:11]
	v_cndmask_b32_e64 v57, v57, v53, s[10:11]
	s_add_u32 s64, s62, 0x40000
	s_addc_u32 s65, s63, 0
	global_store_dwordx4 v251, v[62:65], s[64:65]
	global_store_dwordx4 v163, v[54:57], s[64:65]
	s_waitcnt vmcnt(15)
	v_lshlrev_b32_e32 v172, 16, v246
	v_and_b32_e32 v173, 0xffff0000, v246
	v_add_f32_e32 v46, v46, v172
	v_add_f32_e32 v47, v47, v173
	v_lshlrev_b32_e32 v172, 16, v247
	v_and_b32_e32 v173, 0xffff0000, v247
	v_add_f32_e32 v48, v48, v172
	v_add_f32_e32 v49, v49, v173
	v_lshlrev_b32_e32 v172, 16, v248
	v_and_b32_e32 v173, 0xffff0000, v248
	v_add_f32_e32 v42, v42, v172
	v_add_f32_e32 v43, v43, v173
	v_lshlrev_b32_e32 v172, 16, v249
	v_and_b32_e32 v173, 0xffff0000, v249
	v_add_f32_e32 v44, v44, v172
	v_add_f32_e32 v45, v45, v173
	v_mul_f32_e32 v172, v47, v47
	v_mul_f32_e32 v173, v49, v49
	v_mul_f32_e32 v188, v43, v43
	v_mul_f32_e32 v189, v45, v45
	v_fmac_f32_e32 v172, v46, v46
	v_fmac_f32_e32 v173, v48, v48
	v_fmac_f32_e32 v188, v42, v42
	v_fmac_f32_e32 v189, v44, v44
	v_add_f32_e32 v172, v172, v173
	v_add_f32_e32 v188, v188, v189
	v_add_f32_e32 v172, v172, v188
	v_mov_b32_e32 v169, v172
	v_cvt_pk_bf16_f32 v46, v46, v47
	v_cvt_pk_bf16_f32 v47, v48, v49
	v_cvt_pk_bf16_f32 v48, v42, v43
	v_cvt_pk_bf16_f32 v49, v44, v45
	v_lshlrev_b32_e32 v172, 16, v198
	v_and_b32_e32 v173, 0xffff0000, v198
	v_add_f32_e32 v38, v38, v172
	v_add_f32_e32 v39, v39, v173
	v_lshlrev_b32_e32 v172, 16, v199
	v_and_b32_e32 v173, 0xffff0000, v199
	v_add_f32_e32 v40, v40, v172
	v_add_f32_e32 v41, v41, v173
	v_lshlrev_b32_e32 v172, 16, v200
	v_and_b32_e32 v173, 0xffff0000, v200
	v_add_f32_e32 v34, v34, v172
	v_add_f32_e32 v35, v35, v173
	v_lshlrev_b32_e32 v172, 16, v201
	v_and_b32_e32 v173, 0xffff0000, v201
	v_add_f32_e32 v36, v36, v172
	v_add_f32_e32 v37, v37, v173
	v_mul_f32_e32 v172, v39, v39
	v_mul_f32_e32 v173, v41, v41
	v_mul_f32_e32 v188, v35, v35
	v_mul_f32_e32 v189, v37, v37
	v_fmac_f32_e32 v172, v38, v38
	v_fmac_f32_e32 v173, v40, v40
	v_fmac_f32_e32 v188, v34, v34
	v_fmac_f32_e32 v189, v36, v36
	v_add_f32_e32 v172, v172, v173
	v_add_f32_e32 v188, v188, v189
	v_add_f32_e32 v172, v172, v188
	v_add_f32_e32 v169, v169, v172
	v_cvt_pk_bf16_f32 v38, v38, v39
	v_cvt_pk_bf16_f32 v39, v40, v41
	v_cvt_pk_bf16_f32 v40, v34, v35
	v_cvt_pk_bf16_f32 v41, v36, v37
	v_cndmask_b32_e64 v42, v46, v38, s[10:11]
	v_cndmask_b32_e64 v43, v47, v39, s[10:11]
	v_cndmask_b32_e64 v44, v48, v40, s[10:11]
	v_cndmask_b32_e64 v45, v49, v41, s[10:11]
	v_mov_b32_dpp v34, v42 quad_perm:[1,0,3,2] row_mask:0xf bank_mask:0xf
	v_mov_b32_dpp v35, v43 quad_perm:[1,0,3,2] row_mask:0xf bank_mask:0xf
	v_mov_b32_dpp v36, v44 quad_perm:[1,0,3,2] row_mask:0xf bank_mask:0xf
	v_mov_b32_dpp v37, v45 quad_perm:[1,0,3,2] row_mask:0xf bank_mask:0xf
	v_cndmask_b32_e64 v46, v34, v46, s[10:11]
	v_cndmask_b32_e64 v47, v35, v47, s[10:11]
	v_cndmask_b32_e64 v48, v36, v48, s[10:11]
	v_cndmask_b32_e64 v49, v37, v49, s[10:11]
	v_cndmask_b32_e64 v38, v38, v34, s[10:11]
	v_cndmask_b32_e64 v39, v39, v35, s[10:11]
	v_cndmask_b32_e64 v40, v40, v36, s[10:11]
	v_cndmask_b32_e64 v41, v41, v37, s[10:11]
	s_add_u32 s64, s62, 0x48000
	s_addc_u32 s65, s63, 0
	global_store_dwordx4 v251, v[46:49], s[64:65]
	global_store_dwordx4 v163, v[38:41], s[64:65]
	s_waitcnt vmcnt(15)
; #define LAS __attribute__((address_space(3)))
; __device__ __forceinline__ float bf_lo(unsigned w) { return __uint_as_float(w << 16); }
; __device__ __forceinline__ float bf_hi(unsigned w) { return __uint_as_float(w & 0xffff0000u); }
; __device__ __forceinline__ unsigned cvt_pk_bf16(float lo, float hi) { unsigned r; asm volatile("v_cvt_pk_bf16_f32 %0, %1, %2" : "=v"(r) : "v"(lo), "v"(hi)); return r; }
;     __device__ __forceinline__ void operator()(const f32x4 (&acc)[2][2][4][2], const Unit& u, int wr, int wc, int fr, int fq) const {
;     ...
;             for (int m = 2 * mh; m < 2 * mh + 2; ++m) { const int rowb = u.pm * BM + ai * HALF + wr * 64 + m * 16;
; #pragma unroll
;                 for (int i = 0; i < 2; ++i) bs[m][i] = *(const u32x4*)(xb + (size_t)(rowb + rr + 8 * i) * DM + colw + cc * 8); }
; #pragma unroll
;             for (int m = 2 * mh; m < 2 * mh + 2; ++m) {
;                 const int rowb = u.pm * BM + ai * HALF + wr * 64 + m * 16; float q = 0.f;
; #pragma unroll
;                 for (int i = 0; i < 2; ++i) *(LAS u32x4*)(sl + (rr + 8 * i) * 144 + cc * 16) = bs[m][i];
; #pragma unroll
;                 for (int bj = 0; bj < 2; ++bj) {
;                     const u32x4 b4 = *(const LAS u32x4*)(sl + fr * 144 + bj * 64 + fq * 16);
;                     const f32x4 a0 = acc[ai][bj][m][0], a1 = acc[ai][bj][m][1];
;                     const float o0 = bf_lo(b4.x) + a0[0], o1 = bf_hi(b4.x) + a0[1], o2 = bf_lo(b4.y) + a0[2], o3 = bf_hi(b4.y) + a0[3];
;                     const float o4 = bf_lo(b4.z) + a1[0], o5 = bf_hi(b4.z) + a1[1], o6 = bf_lo(b4.w) + a1[2], o7 = bf_hi(b4.w) + a1[3];
;                     q += ((o0 * o0 + o1 * o1) + (o2 * o2 + o3 * o3)) + ((o4 * o4 + o5 * o5) + (o6 * o6 + o7 * o7));
;                     u32x4 w; w.x = cvt_pk_bf16(o0, o1); w.y = cvt_pk_bf16(o2, o3); w.z = cvt_pk_bf16(o4, o5); w.w = cvt_pk_bf16(o6, o7);
;                     *(LAS u32x4*)(sl + fr * 144 + bj * 64 + fq * 16) = w;
;                 }
	v_lshlrev_b32_e32 v172, 16, v202
	v_and_b32_e32 v173, 0xffff0000, v202
	v_add_f32_e32 v30, v30, v172
	v_add_f32_e32 v31, v31, v173
	v_lshlrev_b32_e32 v172, 16, v203
	v_and_b32_e32 v173, 0xffff0000, v203
	v_add_f32_e32 v32, v32, v172
	v_add_f32_e32 v33, v33, v173
	v_lshlrev_b32_e32 v172, 16, v204
	v_and_b32_e32 v173, 0xffff0000, v204
	v_add_f32_e32 v26, v26, v172
	v_add_f32_e32 v27, v27, v173
	v_lshlrev_b32_e32 v172, 16, v205
	v_and_b32_e32 v173, 0xffff0000, v205
	v_add_f32_e32 v28, v28, v172
	v_add_f32_e32 v29, v29, v173
	v_mul_f32_e32 v172, v31, v31
	v_mul_f32_e32 v173, v33, v33
	v_mul_f32_e32 v188, v27, v27
	v_mul_f32_e32 v189, v29, v29
	v_fmac_f32_e32 v172, v30, v30
	v_fmac_f32_e32 v173, v32, v32
	v_fmac_f32_e32 v188, v26, v26
	v_fmac_f32_e32 v189, v28, v28
	v_add_f32_e32 v172, v172, v173
	v_add_f32_e32 v188, v188, v189
	v_add_f32_e32 v172, v172, v188
	v_mov_b32_e32 v170, v172
	v_cvt_pk_bf16_f32 v30, v30, v31
	v_cvt_pk_bf16_f32 v31, v32, v33
	v_cvt_pk_bf16_f32 v32, v26, v27
	v_cvt_pk_bf16_f32 v33, v28, v29
	v_lshlrev_b32_e32 v172, 16, v130
	v_and_b32_e32 v173, 0xffff0000, v130
	v_add_f32_e32 v22, v22, v172
	v_add_f32_e32 v23, v23, v173
	v_lshlrev_b32_e32 v172, 16, v131
	v_and_b32_e32 v173, 0xffff0000, v131
	v_add_f32_e32 v24, v24, v172
	v_add_f32_e32 v25, v25, v173
	v_lshlrev_b32_e32 v172, 16, v132
	v_and_b32_e32 v173, 0xffff0000, v132
	v_add_f32_e32 v18, v18, v172
	v_add_f32_e32 v19, v19, v173
	v_lshlrev_b32_e32 v172, 16, v133
	v_and_b32_e32 v173, 0xffff0000, v133
	v_add_f32_e32 v20, v20, v172
	v_add_f32_e32 v21, v21, v173
	v_mul_f32_e32 v172, v23, v23
	v_mul_f32_e32 v173, v25, v25
	v_mul_f32_e32 v188, v19, v19
	v_mul_f32_e32 v189, v21, v21
	v_fmac_f32_e32 v172, v22, v22
	v_fmac_f32_e32 v173, v24, v24
	v_fmac_f32_e32 v188, v18, v18
	v_fmac_f32_e32 v189, v20, v20
	v_add_f32_e32 v172, v172, v173
	v_add_f32_e32 v188, v188, v189
	v_add_f32_e32 v172, v172, v188
	v_add_f32_e32 v170, v170, v172
	v_cvt_pk_bf16_f32 v22, v22, v23
	v_cvt_pk_bf16_f32 v23, v24, v25
	v_cvt_pk_bf16_f32 v24, v18, v19
	v_cvt_pk_bf16_f32 v25, v20, v21
	v_cndmask_b32_e64 v26, v30, v22, s[10:11]
	v_cndmask_b32_e64 v27, v31, v23, s[10:11]
	v_cndmask_b32_e64 v28, v32, v24, s[10:11]
	v_cndmask_b32_e64 v29, v33, v25, s[10:11]
	v_mov_b32_dpp v18, v26 quad_perm:[1,0,3,2] row_mask:0xf bank_mask:0xf
	v_mov_b32_dpp v19, v27 quad_perm:[1,0,3,2] row_mask:0xf bank_mask:0xf
	v_mov_b32_dpp v20, v28 quad_perm:[1,0,3,2] row_mask:0xf bank_mask:0xf
	v_mov_b32_dpp v21, v29 quad_perm:[1,0,3,2] row_mask:0xf bank_mask:0xf
	v_cndmask_b32_e64 v30, v18, v30, s[10:11]
	v_cndmask_b32_e64 v31, v19, v31, s[10:11]
	v_cndmask_b32_e64 v32, v20, v32, s[10:11]
	v_cndmask_b32_e64 v33, v21, v33, s[10:11]
	v_cndmask_b32_e64 v22, v22, v18, s[10:11]
	v_cndmask_b32_e64 v23, v23, v19, s[10:11]
	v_cndmask_b32_e64 v24, v24, v20, s[10:11]
	v_cndmask_b32_e64 v25, v25, v21, s[10:11]
	s_add_u32 s64, s62, 0x50000
	s_addc_u32 s65, s63, 0
	global_store_dwordx4 v251, v[30:33], s[64:65]
	global_store_dwordx4 v163, v[22:25], s[64:65]
	s_waitcnt vmcnt(15)
; #define LAS __attribute__((address_space(3)))
;     __device__ __forceinline__ void operator()(const f32x4 (&acc)[2][2][4][2], const Unit& u, int wr, int wc, int fr, int fq) const {
;     ...
;             for (int m = 2 * mh; m < 2 * mh + 2; ++m) { const int rowb = u.pm * BM + ai * HALF + wr * 64 + m * 16;
; #pragma unroll
;                 for (int i = 0; i < 2; ++i) bs[m][i] = *(const u32x4*)(xb + (size_t)(rowb + rr + 8 * i) * DM + colw + cc * 8); }
; #pragma unroll
;             for (int m = 2 * mh; m < 2 * mh + 2; ++m) {
;                 const int rowb = u.pm * BM + ai * HALF + wr * 64 + m * 16; float q = 0.f;
; #pragma unroll
;                 for (int i = 0; i < 2; ++i) *(LAS u32x4*)(sl + (rr + 8 * i) * 144 + cc * 16) = bs[m][i];
; #pragma unroll
;                 for (int bj = 0; bj < 2; ++bj) {
;                     const u32x4 b4 = *(const LAS u32x4*)(sl + fr * 144 + bj * 64 + fq * 16);
;                     const f32x4 a0 = acc[ai][bj][m][0], a1 = acc[ai][bj][m][1];
;                     const float o0 = bf_lo(b4.x) + a0[0], o1 = bf_hi(b4.x) + a0[1], o2 = bf_lo(b4.y) + a0[2], o3 = bf_hi(b4.y) + a0[3];
;                     const float o4 = bf_lo(b4.z) + a1[0], o5 = bf_hi(b4.z) + a1[1], o6 = bf_lo(b4.w) + a1[2], o7 = bf_hi(b4.w) + a1[3];
;                     q += ((o0 * o0 + o1 * o1) + (o2 * o2 + o3 * o3)) + ((o4 * o4 + o5 * o5) + (o6 * o6 + o7 * o7));
;                     u32x4 w; w.x = cvt_pk_bf16(o0, o1); w.y = cvt_pk_bf16(o2, o3); w.z = cvt_pk_bf16(o4, o5); w.w = cvt_pk_bf16(o6, o7);
;                     *(LAS u32x4*)(sl + fr * 144 + bj * 64 + fq * 16) = w;
;                 }
; #pragma unroll
;                 for (int i = 0; i < 2; ++i) { const u32x4 qv = *(const LAS u32x4*)(sl + (rr + 8 * i) * 144 + cc * 16);
;                     *(u32x4*)(xb + (size_t)(rowb + rr + 8 * i) * DM + colw + cc * 8) = qv; }
;                 q += __shfl_xor(q, 16); q += __shfl_xor(q, 32); qs[m] = q;
;             }
;             asm volatile("" ::: "memory");
;             }
;             { const float mine = fq == 0 ? qs[0] : (fq == 1 ? qs[1] : (fq == 2 ? qs[2] : qs[3]));
;               __hip_atomic_fetch_add(ssq + (u.pm * BM + ai * HALF + wr * 64 + 16 * fq + fr), (u64)(mine * 16777216.0f), __ATOMIC_RELAXED, __HIP_MEMORY_SCOPE_AGENT); }
;             asm volatile("" ::: "memory");
;         }
	v_lshlrev_b32_e32 v172, 16, v134
	v_and_b32_e32 v173, 0xffff0000, v134
	v_add_f32_e32 v14, v14, v172
	v_add_f32_e32 v15, v15, v173
	v_lshlrev_b32_e32 v172, 16, v135
	v_and_b32_e32 v173, 0xffff0000, v135
	v_add_f32_e32 v16, v16, v172
	v_add_f32_e32 v17, v17, v173
	v_lshlrev_b32_e32 v172, 16, v136
	v_and_b32_e32 v173, 0xffff0000, v136
	v_add_f32_e32 v10, v10, v172
	v_add_f32_e32 v11, v11, v173
	v_lshlrev_b32_e32 v172, 16, v137
	v_and_b32_e32 v173, 0xffff0000, v137
	v_add_f32_e32 v12, v12, v172
	v_add_f32_e32 v13, v13, v173
	v_mul_f32_e32 v172, v15, v15
	v_mul_f32_e32 v173, v17, v17
	v_mul_f32_e32 v188, v11, v11
	v_mul_f32_e32 v189, v13, v13
	v_fmac_f32_e32 v172, v14, v14
	v_fmac_f32_e32 v173, v16, v16
	v_fmac_f32_e32 v188, v10, v10
	v_fmac_f32_e32 v189, v12, v12
	v_add_f32_e32 v172, v172, v173
	v_add_f32_e32 v188, v188, v189
	v_add_f32_e32 v172, v172, v188
	v_mov_b32_e32 v171, v172
	v_cvt_pk_bf16_f32 v14, v14, v15
	v_cvt_pk_bf16_f32 v15, v16, v17
	v_cvt_pk_bf16_f32 v16, v10, v11
	v_cvt_pk_bf16_f32 v17, v12, v13
	v_lshlrev_b32_e32 v172, 16, v164
	v_and_b32_e32 v173, 0xffff0000, v164
	v_add_f32_e32 v6, v6, v172
	v_add_f32_e32 v7, v7, v173
	v_lshlrev_b32_e32 v172, 16, v165
	v_and_b32_e32 v173, 0xffff0000, v165
	v_add_f32_e32 v8, v8, v172
	v_add_f32_e32 v9, v9, v173
	v_lshlrev_b32_e32 v172, 16, v166
	v_and_b32_e32 v173, 0xffff0000, v166
	v_add_f32_e32 v2, v2, v172
	v_add_f32_e32 v3, v3, v173
	v_lshlrev_b32_e32 v172, 16, v167
	v_and_b32_e32 v173, 0xffff0000, v167
	v_add_f32_e32 v4, v4, v172
	v_add_f32_e32 v5, v5, v173
	v_mul_f32_e32 v172, v7, v7
	v_mul_f32_e32 v173, v9, v9
	v_mul_f32_e32 v188, v3, v3
	v_mul_f32_e32 v189, v5, v5
	v_fmac_f32_e32 v172, v6, v6
	v_fmac_f32_e32 v173, v8, v8
	v_fmac_f32_e32 v188, v2, v2
	v_fmac_f32_e32 v189, v4, v4
	v_add_f32_e32 v172, v172, v173
	v_add_f32_e32 v188, v188, v189
	v_add_f32_e32 v172, v172, v188
	v_add_f32_e32 v171, v171, v172
	v_cvt_pk_bf16_f32 v6, v6, v7
	v_cvt_pk_bf16_f32 v7, v8, v9
	v_cvt_pk_bf16_f32 v8, v2, v3
	v_cvt_pk_bf16_f32 v9, v4, v5
	v_cndmask_b32_e64 v10, v14, v6, s[10:11]
	v_cndmask_b32_e64 v11, v15, v7, s[10:11]
	v_cndmask_b32_e64 v12, v16, v8, s[10:11]
	v_cndmask_b32_e64 v13, v17, v9, s[10:11]
	v_mov_b32_dpp v2, v10 quad_perm:[1,0,3,2] row_mask:0xf bank_mask:0xf
	v_mov_b32_dpp v3, v11 quad_perm:[1,0,3,2] row_mask:0xf bank_mask:0xf
	v_mov_b32_dpp v4, v12 quad_perm:[1,0,3,2] row_mask:0xf bank_mask:0xf
	v_mov_b32_dpp v5, v13 quad_perm:[1,0,3,2] row_mask:0xf bank_mask:0xf
	v_cndmask_b32_e64 v14, v2, v14, s[10:11]
	v_cndmask_b32_e64 v15, v3, v15, s[10:11]
	v_cndmask_b32_e64 v16, v4, v16, s[10:11]
	v_cndmask_b32_e64 v17, v5, v17, s[10:11]
	v_cndmask_b32_e64 v6, v6, v2, s[10:11]
	v_cndmask_b32_e64 v7, v7, v3, s[10:11]
	v_cndmask_b32_e64 v8, v8, v4, s[10:11]
	v_cndmask_b32_e64 v9, v9, v5, s[10:11]
	s_add_u32 s64, s62, 0x58000
	s_addc_u32 s65, s63, 0
	global_store_dwordx4 v251, v[14:17], s[64:65]
	global_store_dwordx4 v163, v[6:9], s[64:65]
	v_xor_b32_e32 v172, 16, v177
	v_lshlrev_b32_e32 v172, 2, v172
	v_xor_b32_e32 v173, 32, v177
	v_lshlrev_b32_e32 v173, 2, v173
	ds_bpermute_b32 v10, v172, v168
	ds_bpermute_b32 v11, v172, v169
	ds_bpermute_b32 v12, v172, v170
	ds_bpermute_b32 v13, v172, v171
	s_waitcnt lgkmcnt(3)
	v_add_f32_e32 v168, v168, v10
	s_waitcnt lgkmcnt(2)
	v_add_f32_e32 v169, v169, v11
	s_waitcnt lgkmcnt(1)
	v_add_f32_e32 v170, v170, v12
	s_waitcnt lgkmcnt(0)
	v_add_f32_e32 v171, v171, v13
	ds_bpermute_b32 v10, v173, v168
	ds_bpermute_b32 v11, v173, v169
	ds_bpermute_b32 v12, v173, v170
	ds_bpermute_b32 v13, v173, v171
	s_waitcnt lgkmcnt(3)
	v_add_f32_e32 v168, v168, v10
	s_waitcnt lgkmcnt(2)
	v_add_f32_e32 v169, v169, v11
	s_waitcnt lgkmcnt(1)
	v_add_f32_e32 v170, v170, v12
	s_waitcnt lgkmcnt(0)
	v_add_f32_e32 v171, v171, v13
	v_bfe_u32 v188, v177, 4, 2
	v_cmp_eq_u32_e64 s[64:65], 1, v188
	v_cmp_eq_u32_e64 s[98:99], 2, v188
	v_cmp_eq_u32_e32 vcc, 3, v188
	s_nop 1
	v_cndmask_b32_e64 v189, v168, v169, s[64:65]
	v_cndmask_b32_e64 v189, v189, v170, s[98:99]
	v_cndmask_b32_e32 v189, v189, v171, vcc
	v_mul_f32_e32 v189, 0x4b800000, v189
	v_trunc_f32_e32 v189, v189
	v_mul_f32_e32 v188, 0x2f800000, v189
	v_floor_f32_e32 v188, v188
	v_fmac_f32_e32 v189, 0xcf800000, v188
	v_cvt_u32_f32_e32 v172, v189
	v_cvt_u32_f32_e32 v173, v188
	s_andn2_b64 vcc, exec, s[38:39]
	s_mov_b64 s[26:27], -1
	global_atomic_add_x2 v250, v[172:173], s[100:101] offset:1024
	s_cbranch_vccnz .LBB0_580
	s_andn2_b64 vcc, exec, s[28:29]
	s_cbranch_vccnz .LBB0_579
	s_barrier
	s_branch .LBB0_579
